# v073: v011 + packed f32 mul/add in SwiGLU epilogue + diff fast path: V(t+1) frag reads spread over PV(t) gaps + first staging block moved behind QK(t) burst
# speedup vs baseline: 1.0202x; 1.0042x over previous
; __device__ __forceinline__ unsigned cvt_pk_bf16(float lo, float hi) { unsigned r; asm volatile("v_cvt_pk_bf16_f32 %0, %1, %2" : "=v"(r) : "v"(lo), "v"(hi)); return r; }
;     __device__ __forceinline__ static float sg(float g, float u) { return g * u * __builtin_amdgcn_rcpf(1.0f + __builtin_amdgcn_exp2f(-1.4426950408889634f * g)); }
;     __device__ __forceinline__ void operator()(const f32x4 (&acc)[2][2][4][2], const Unit& u, int wr, int wc, int fr, int fq) const {
;         const int row0 = u.pm * BM + wr * 64 + fr, col0 = u.pn * BM + wc * 32 + 8 * fq, j0 = u.pn * HALF + wc * 32 + 8 * fq;
;         const float* bp = bt + (size_t)((u.pm * BM) >> 12) * (2 * 2816) + col0;
;         f32x4 bv[2][2];
; #pragma unroll
;         for (int bj = 0; bj < 2; ++bj)
; #pragma unroll
;             for (int n = 0; n < 2; ++n) bv[bj][n] = *(const f32x4*)(bp + bj * HALF + 4 * n);
; #pragma unroll
;         for (int ai = 0; ai < 2; ++ai)
; #pragma unroll
;             for (int m = 0; m < 4; ++m) { const int row = row0 + ai * HALF + m * 16;
;                 const float rstd = __builtin_amdgcn_rsqf(SS[row] * (1.0f / 1024.0f) + 1e-6f);
;                 const f32x4 g0 = acc[ai][0][m][0] * rstd + bv[0][0], g1 = acc[ai][0][m][1] * rstd + bv[0][1], u0 = acc[ai][1][m][0] * rstd + bv[1][0], u1 = acc[ai][1][m][1] * rstd + bv[1][1];
;                 u32x4 w; w.x = cvt_pk_bf16(sg(g0[0], u0[0]), sg(g0[1], u0[1])); w.y = cvt_pk_bf16(sg(g0[2], u0[2]), sg(g0[3], u0[3]));
;                 w.z = cvt_pk_bf16(sg(g1[0], u1[0]), sg(g1[1], u1[1])); w.w = cvt_pk_bf16(sg(g1[2], u1[2]), sg(g1[3], u1[3]));
;                 *(u32x4*)(O + (size_t)row * ldc + j0) = w; }
.LBB0_804:
	s_lshl_b32 s0, s70, 8
	v_mov_b32_e32 v129, v204
	s_add_i32 s0, s0, s60
	s_lshl_b32 s1, s71, 8
	v_lshrrev_b32_e32 v128, 1, v129
	v_and_or_b32 v160, v129, 15, s0
	s_or_b32 s1, s1, s16
	v_and_b32_e32 v166, 24, v128
	v_ashrrev_i32_e32 v161, 31, v160
	v_or_b32_e32 v128, s1, v166
	s_lshl_b32 s1, s71, 7
	v_lshl_add_u64 v[162:163], v[160:161], 2, s[10:11]
	s_or_b32 s22, s1, s16
	s_ashr_i32 s1, s70, 4
	s_mov_b32 s76, 0xbfb8aa3b
	s_mov_b32 s77, 0xbfb8aa3b
	s_mov_b32 s86, 1.0
	s_mov_b32 s87, 1.0
	global_load_dword v161, v[162:163], off
	global_load_dword v182, v[162:163], off offset:64
	global_load_dword v183, v[162:163], off offset:128
	global_load_dword v184, v[162:163], off offset:192
	global_load_dword v185, v[162:163], off offset:512
	global_load_dword v186, v[162:163], off offset:576
	global_load_dword v187, v[162:163], off offset:640
	global_load_dword v188, v[162:163], off offset:704
	s_mul_hi_i32 s23, s1, 0x5800
	s_mulk_i32 s1, 0x5800
	s_add_u32 s0, s17, s1
	s_addc_u32 s1, s36, s23
	v_ashrrev_i32_e32 v129, 31, v128
	v_lshl_add_u64 v[128:129], v[128:129], 2, s[0:1]
	global_load_dwordx4 v[140:143], v[128:129], off
	global_load_dwordx4 v[136:139], v[128:129], off offset:16
	global_load_dwordx4 v[132:135], v[128:129], off offset:512
	s_nop 0
	global_load_dwordx4 v[128:131], v[128:129], off offset:528
	v_or_b32_e32 v166, s22, v166
	v_mov_b64_e32 v[164:165], s[20:21]
	v_ashrrev_i32_e32 v167, 31, v166
	v_mad_i64_i32 v[174:175], s[0:1], v160, s67, v[164:165]
	v_or_b32_e32 v176, 16, v160
	v_lshlrev_b64 v[166:167], 1, v[166:167]
	v_ashrrev_i32_e32 v177, 31, v176
	v_lshl_add_u64 v[174:175], v[174:175], 0, v[166:167]
	v_lshl_add_u64 v[180:181], v[176:177], 2, s[10:11]
	s_and_b64 vcc, exec, s[6:7]
	s_mov_b64 s[6:7], -1
	s_waitcnt vmcnt(0)
	v_fmamk_f32 v161, v161, 0x3a800000, v172
	v_rsq_f32_e32 v178, v161
	s_nop 0
	v_pk_fma_f32 v[126:127], v[126:127], v[178:179], v[138:139] op_sel_hi:[1,0,1]
	v_pk_fma_f32 v[122:123], v[122:123], v[178:179], v[142:143] op_sel_hi:[1,0,1]
	v_pk_fma_f32 v[114:115], v[114:115], v[178:179], v[130:131] op_sel_hi:[1,0,1]
	v_pk_fma_f32 v[120:121], v[120:121], v[178:179], v[140:141] op_sel_hi:[1,0,1]
	v_pk_fma_f32 v[124:125], v[124:125], v[178:179], v[136:137] op_sel_hi:[1,0,1]
	v_pk_fma_f32 v[118:119], v[118:119], v[178:179], v[134:135] op_sel_hi:[1,0,1]
	v_pk_fma_f32 v[116:117], v[116:117], v[178:179], v[132:133] op_sel_hi:[1,0,1]
	v_pk_fma_f32 v[112:113], v[112:113], v[178:179], v[128:129] op_sel_hi:[1,0,1]
	v_pk_mul_f32 v[116:117], v[120:121], v[116:117]
	v_pk_mul_f32 v[118:119], v[122:123], v[118:119]
	v_pk_mul_f32 v[112:113], v[124:125], v[112:113]
	v_pk_mul_f32 v[114:115], v[126:127], v[114:115]
	v_pk_mul_f32 v[120:121], v[120:121], s[76:77]
	v_pk_mul_f32 v[122:123], v[122:123], s[76:77]
	v_pk_mul_f32 v[124:125], v[124:125], s[76:77]
	v_pk_mul_f32 v[126:127], v[126:127], s[76:77]
	v_exp_f32_e32 v127, v127
	v_exp_f32_e32 v120, v120
	v_exp_f32_e32 v121, v121
	v_exp_f32_e32 v122, v122
	v_exp_f32_e32 v123, v123
	v_exp_f32_e32 v124, v124
	v_exp_f32_e32 v125, v125
	v_exp_f32_e32 v126, v126
	v_pk_add_f32 v[120:121], v[120:121], s[86:87]
	v_pk_add_f32 v[122:123], v[122:123], s[86:87]
	v_pk_add_f32 v[124:125], v[124:125], s[86:87]
	v_pk_add_f32 v[126:127], v[126:127], s[86:87]
	v_rcp_f32_e32 v127, v127
	v_rcp_f32_e32 v120, v120
	v_rcp_f32_e32 v121, v121
	v_rcp_f32_e32 v122, v122
	v_rcp_f32_e32 v123, v123
	v_rcp_f32_e32 v124, v124
	v_rcp_f32_e32 v125, v125
	v_rcp_f32_e32 v126, v126
	v_pk_mul_f32 v[116:117], v[116:117], v[120:121]
	v_pk_mul_f32 v[118:119], v[118:119], v[122:123]
	v_pk_mul_f32 v[112:113], v[112:113], v[124:125]
	v_pk_mul_f32 v[114:115], v[114:115], v[126:127]
	v_cvt_pk_bf16_f32 v120, v116, v117
	v_cvt_pk_bf16_f32 v121, v118, v119
	v_cvt_pk_bf16_f32 v122, v112, v113
	v_cvt_pk_bf16_f32 v123, v114, v115
	global_store_dwordx4 v[174:175], v[120:123], off
	s_nop 0
	s_nop 0
	v_or_b32_e32 v112, 32, v160
	v_mad_i64_i32 v[114:115], s[0:1], v176, s67, v[164:165]
	v_lshl_add_u64 v[114:115], v[114:115], 0, v[166:167]
	v_fmamk_f32 v113, v182, 0x3a800000, v172
	v_rsq_f32_e32 v116, v113
	v_ashrrev_i32_e32 v113, 31, v112
	v_lshl_add_u64 v[118:119], v[112:113], 2, s[10:11]
	v_pk_fma_f32 v[106:107], v[106:107], v[116:117], v[138:139] op_sel_hi:[1,0,1]
	v_pk_fma_f32 v[98:99], v[98:99], v[116:117], v[130:131] op_sel_hi:[1,0,1]
	v_pk_fma_f32 v[110:111], v[110:111], v[116:117], v[142:143] op_sel_hi:[1,0,1]
	v_pk_fma_f32 v[108:109], v[108:109], v[116:117], v[140:141] op_sel_hi:[1,0,1]
	v_pk_fma_f32 v[104:105], v[104:105], v[116:117], v[136:137] op_sel_hi:[1,0,1]
	v_pk_fma_f32 v[102:103], v[102:103], v[116:117], v[134:135] op_sel_hi:[1,0,1]
	v_pk_fma_f32 v[100:101], v[100:101], v[116:117], v[132:133] op_sel_hi:[1,0,1]
	v_pk_fma_f32 v[96:97], v[96:97], v[116:117], v[128:129] op_sel_hi:[1,0,1]
	v_pk_mul_f32 v[100:101], v[108:109], v[100:101]
	v_pk_mul_f32 v[102:103], v[110:111], v[102:103]
	v_pk_mul_f32 v[96:97], v[104:105], v[96:97]
	v_pk_mul_f32 v[98:99], v[106:107], v[98:99]
	v_pk_mul_f32 v[108:109], v[108:109], s[76:77]
	v_pk_mul_f32 v[110:111], v[110:111], s[76:77]
	v_pk_mul_f32 v[104:105], v[104:105], s[76:77]
	v_pk_mul_f32 v[106:107], v[106:107], s[76:77]
	v_exp_f32_e32 v107, v107
	v_exp_f32_e32 v108, v108
	v_exp_f32_e32 v109, v109
	v_exp_f32_e32 v110, v110
	v_exp_f32_e32 v111, v111
	v_exp_f32_e32 v104, v104
	v_exp_f32_e32 v105, v105
	v_exp_f32_e32 v106, v106
	v_pk_add_f32 v[108:109], v[108:109], s[86:87]
	v_pk_add_f32 v[110:111], v[110:111], s[86:87]
	v_pk_add_f32 v[104:105], v[104:105], s[86:87]
	v_pk_add_f32 v[106:107], v[106:107], s[86:87]
	v_rcp_f32_e32 v107, v107
	v_rcp_f32_e32 v108, v108
	v_rcp_f32_e32 v109, v109
; __device__ __forceinline__ unsigned cvt_pk_bf16(float lo, float hi) { unsigned r; asm volatile("v_cvt_pk_bf16_f32 %0, %1, %2" : "=v"(r) : "v"(lo), "v"(hi)); return r; }
;     __device__ __forceinline__ static float sg(float g, float u) { return g * u * __builtin_amdgcn_rcpf(1.0f + __builtin_amdgcn_exp2f(-1.4426950408889634f * g)); }
;     __device__ __forceinline__ void operator()(const f32x4 (&acc)[2][2][4][2], const Unit& u, int wr, int wc, int fr, int fq) const {
;     ...
;             for (int m = 0; m < 4; ++m) { const int row = row0 + ai * HALF + m * 16;
;                 const float rstd = __builtin_amdgcn_rsqf(SS[row] * (1.0f / 1024.0f) + 1e-6f);
;                 const f32x4 g0 = acc[ai][0][m][0] * rstd + bv[0][0], g1 = acc[ai][0][m][1] * rstd + bv[0][1], u0 = acc[ai][1][m][0] * rstd + bv[1][0], u1 = acc[ai][1][m][1] * rstd + bv[1][1];
;                 u32x4 w; w.x = cvt_pk_bf16(sg(g0[0], u0[0]), sg(g0[1], u0[1])); w.y = cvt_pk_bf16(sg(g0[2], u0[2]), sg(g0[3], u0[3]));
;                 w.z = cvt_pk_bf16(sg(g1[0], u1[0]), sg(g1[1], u1[1])); w.w = cvt_pk_bf16(sg(g1[2], u1[2]), sg(g1[3], u1[3]));
;                 *(u32x4*)(O + (size_t)row * ldc + j0) = w; }
	v_rcp_f32_e32 v110, v110
	v_rcp_f32_e32 v111, v111
	v_rcp_f32_e32 v104, v104
	v_rcp_f32_e32 v105, v105
	v_rcp_f32_e32 v106, v106
	v_pk_mul_f32 v[100:101], v[100:101], v[108:109]
	v_pk_mul_f32 v[102:103], v[102:103], v[110:111]
	v_pk_mul_f32 v[96:97], v[96:97], v[104:105]
	v_pk_mul_f32 v[98:99], v[98:99], v[106:107]
	v_cvt_pk_bf16_f32 v104, v100, v101
	v_cvt_pk_bf16_f32 v105, v102, v103
	v_cvt_pk_bf16_f32 v106, v96, v97
	v_cvt_pk_bf16_f32 v107, v98, v99
	global_store_dwordx4 v[114:115], v[104:107], off
	s_nop 0
	s_nop 0
	v_or_b32_e32 v96, 48, v160
	v_mad_i64_i32 v[98:99], s[0:1], v112, s67, v[164:165]
	v_lshl_add_u64 v[98:99], v[98:99], 0, v[166:167]
	v_fmamk_f32 v97, v183, 0x3a800000, v172
	v_rsq_f32_e32 v100, v97
	v_ashrrev_i32_e32 v97, 31, v96
	v_lshl_add_u64 v[102:103], v[96:97], 2, s[10:11]
	v_pk_fma_f32 v[90:91], v[90:91], v[100:101], v[138:139] op_sel_hi:[1,0,1]
	v_pk_fma_f32 v[82:83], v[82:83], v[100:101], v[130:131] op_sel_hi:[1,0,1]
	v_pk_fma_f32 v[94:95], v[94:95], v[100:101], v[142:143] op_sel_hi:[1,0,1]
	v_pk_fma_f32 v[92:93], v[92:93], v[100:101], v[140:141] op_sel_hi:[1,0,1]
	v_pk_fma_f32 v[88:89], v[88:89], v[100:101], v[136:137] op_sel_hi:[1,0,1]
	v_pk_fma_f32 v[86:87], v[86:87], v[100:101], v[134:135] op_sel_hi:[1,0,1]
	v_pk_fma_f32 v[84:85], v[84:85], v[100:101], v[132:133] op_sel_hi:[1,0,1]
	v_pk_fma_f32 v[80:81], v[80:81], v[100:101], v[128:129] op_sel_hi:[1,0,1]
	v_pk_mul_f32 v[84:85], v[92:93], v[84:85]
	v_pk_mul_f32 v[86:87], v[94:95], v[86:87]
	v_pk_mul_f32 v[80:81], v[88:89], v[80:81]
	v_pk_mul_f32 v[82:83], v[90:91], v[82:83]
	v_pk_mul_f32 v[92:93], v[92:93], s[76:77]
	v_pk_mul_f32 v[94:95], v[94:95], s[76:77]
	v_pk_mul_f32 v[88:89], v[88:89], s[76:77]
	v_pk_mul_f32 v[90:91], v[90:91], s[76:77]
	v_exp_f32_e32 v91, v91
	v_exp_f32_e32 v92, v92
	v_exp_f32_e32 v93, v93
	v_exp_f32_e32 v94, v94
	v_exp_f32_e32 v95, v95
	v_exp_f32_e32 v88, v88
	v_exp_f32_e32 v89, v89
	v_exp_f32_e32 v90, v90
	v_pk_add_f32 v[92:93], v[92:93], s[86:87]
	v_pk_add_f32 v[94:95], v[94:95], s[86:87]
	v_pk_add_f32 v[88:89], v[88:89], s[86:87]
	v_pk_add_f32 v[90:91], v[90:91], s[86:87]
	v_rcp_f32_e32 v91, v91
	v_rcp_f32_e32 v92, v92
	v_rcp_f32_e32 v93, v93
	v_rcp_f32_e32 v94, v94
	v_rcp_f32_e32 v95, v95
	v_rcp_f32_e32 v88, v88
	v_rcp_f32_e32 v89, v89
	v_rcp_f32_e32 v90, v90
	v_pk_mul_f32 v[84:85], v[84:85], v[92:93]
	v_pk_mul_f32 v[86:87], v[86:87], v[94:95]
	v_pk_mul_f32 v[80:81], v[80:81], v[88:89]
	v_pk_mul_f32 v[82:83], v[82:83], v[90:91]
	v_cvt_pk_bf16_f32 v88, v84, v85
	v_cvt_pk_bf16_f32 v89, v86, v87
	v_cvt_pk_bf16_f32 v90, v80, v81
	v_cvt_pk_bf16_f32 v91, v82, v83
	global_store_dwordx4 v[98:99], v[88:91], off
	s_nop 0
	s_nop 0
	v_mad_i64_i32 v[82:83], s[0:1], v96, s67, v[164:165]
	v_lshl_add_u64 v[82:83], v[82:83], 0, v[166:167]
	v_fmamk_f32 v80, v184, 0x3a800000, v172
	v_rsq_f32_e32 v80, v80
	s_nop 0
	v_pk_fma_f32 v[74:75], v[74:75], v[80:81], v[138:139] op_sel_hi:[1,0,1]
	v_pk_fma_f32 v[66:67], v[66:67], v[80:81], v[130:131] op_sel_hi:[1,0,1]
	v_pk_fma_f32 v[78:79], v[78:79], v[80:81], v[142:143] op_sel_hi:[1,0,1]
	v_pk_fma_f32 v[76:77], v[76:77], v[80:81], v[140:141] op_sel_hi:[1,0,1]
	v_pk_fma_f32 v[72:73], v[72:73], v[80:81], v[136:137] op_sel_hi:[1,0,1]
	v_pk_fma_f32 v[70:71], v[70:71], v[80:81], v[134:135] op_sel_hi:[1,0,1]
	v_pk_fma_f32 v[68:69], v[68:69], v[80:81], v[132:133] op_sel_hi:[1,0,1]
	v_pk_fma_f32 v[64:65], v[64:65], v[80:81], v[128:129] op_sel_hi:[1,0,1]
	v_pk_mul_f32 v[68:69], v[76:77], v[68:69]
	v_pk_mul_f32 v[70:71], v[78:79], v[70:71]
	v_pk_mul_f32 v[64:65], v[72:73], v[64:65]
	v_pk_mul_f32 v[66:67], v[74:75], v[66:67]
	v_pk_mul_f32 v[76:77], v[76:77], s[76:77]
	v_pk_mul_f32 v[78:79], v[78:79], s[76:77]
	v_pk_mul_f32 v[72:73], v[72:73], s[76:77]
	v_pk_mul_f32 v[74:75], v[74:75], s[76:77]
	v_exp_f32_e32 v75, v75
	v_exp_f32_e32 v76, v76
	v_exp_f32_e32 v77, v77
	v_exp_f32_e32 v78, v78
	v_exp_f32_e32 v79, v79
	v_exp_f32_e32 v72, v72
	v_exp_f32_e32 v73, v73
	v_exp_f32_e32 v74, v74
	v_pk_add_f32 v[76:77], v[76:77], s[86:87]
	v_pk_add_f32 v[78:79], v[78:79], s[86:87]
	v_pk_add_f32 v[72:73], v[72:73], s[86:87]
	v_pk_add_f32 v[74:75], v[74:75], s[86:87]
	v_rcp_f32_e32 v75, v75
	v_rcp_f32_e32 v76, v76
	v_rcp_f32_e32 v77, v77
	v_rcp_f32_e32 v78, v78
	v_rcp_f32_e32 v79, v79
	v_rcp_f32_e32 v72, v72
	v_rcp_f32_e32 v73, v73
	v_rcp_f32_e32 v74, v74
	v_pk_mul_f32 v[68:69], v[68:69], v[76:77]
	v_pk_mul_f32 v[70:71], v[70:71], v[78:79]
	v_pk_mul_f32 v[64:65], v[64:65], v[72:73]
	v_pk_mul_f32 v[66:67], v[66:67], v[74:75]
	v_cvt_pk_bf16_f32 v72, v68, v69
	v_cvt_pk_bf16_f32 v73, v70, v71
	v_cvt_pk_bf16_f32 v74, v64, v65
	v_cvt_pk_bf16_f32 v75, v66, v67
	global_store_dwordx4 v[82:83], v[72:75], off
	s_nop 0
	s_nop 0
	v_add_u32_e32 v65, 0x80, v160
	v_mad_i64_i32 v[66:67], s[0:1], v65, s67, v[164:165]
	v_lshl_add_u64 v[66:67], v[66:67], 0, v[166:167]
	v_fmamk_f32 v64, v185, 0x3a800000, v172
	v_rsq_f32_e32 v64, v64
	s_nop 0
	v_pk_fma_f32 v[58:59], v[58:59], v[64:65], v[138:139] op_sel_hi:[1,0,1]
	v_pk_fma_f32 v[50:51], v[50:51], v[64:65], v[130:131] op_sel_hi:[1,0,1]
	v_pk_fma_f32 v[62:63], v[62:63], v[64:65], v[142:143] op_sel_hi:[1,0,1]
	v_pk_fma_f32 v[60:61], v[60:61], v[64:65], v[140:141] op_sel_hi:[1,0,1]
	v_pk_fma_f32 v[56:57], v[56:57], v[64:65], v[136:137] op_sel_hi:[1,0,1]
	v_pk_fma_f32 v[54:55], v[54:55], v[64:65], v[134:135] op_sel_hi:[1,0,1]
	v_pk_fma_f32 v[52:53], v[52:53], v[64:65], v[132:133] op_sel_hi:[1,0,1]
	v_pk_fma_f32 v[48:49], v[48:49], v[64:65], v[128:129] op_sel_hi:[1,0,1]
	v_pk_mul_f32 v[52:53], v[60:61], v[52:53]
	v_pk_mul_f32 v[54:55], v[62:63], v[54:55]
	v_pk_mul_f32 v[48:49], v[56:57], v[48:49]
; __device__ __forceinline__ unsigned cvt_pk_bf16(float lo, float hi) { unsigned r; asm volatile("v_cvt_pk_bf16_f32 %0, %1, %2" : "=v"(r) : "v"(lo), "v"(hi)); return r; }
;     __device__ __forceinline__ static float sg(float g, float u) { return g * u * __builtin_amdgcn_rcpf(1.0f + __builtin_amdgcn_exp2f(-1.4426950408889634f * g)); }
;     __device__ __forceinline__ void operator()(const f32x4 (&acc)[2][2][4][2], const Unit& u, int wr, int wc, int fr, int fq) const {
;     ...
;             for (int m = 0; m < 4; ++m) { const int row = row0 + ai * HALF + m * 16;
;                 const float rstd = __builtin_amdgcn_rsqf(SS[row] * (1.0f / 1024.0f) + 1e-6f);
;                 const f32x4 g0 = acc[ai][0][m][0] * rstd + bv[0][0], g1 = acc[ai][0][m][1] * rstd + bv[0][1], u0 = acc[ai][1][m][0] * rstd + bv[1][0], u1 = acc[ai][1][m][1] * rstd + bv[1][1];
;                 u32x4 w; w.x = cvt_pk_bf16(sg(g0[0], u0[0]), sg(g0[1], u0[1])); w.y = cvt_pk_bf16(sg(g0[2], u0[2]), sg(g0[3], u0[3]));
;                 w.z = cvt_pk_bf16(sg(g1[0], u1[0]), sg(g1[1], u1[1])); w.w = cvt_pk_bf16(sg(g1[2], u1[2]), sg(g1[3], u1[3]));
;                 *(u32x4*)(O + (size_t)row * ldc + j0) = w; }
	v_pk_mul_f32 v[50:51], v[58:59], v[50:51]
	v_pk_mul_f32 v[60:61], v[60:61], s[76:77]
	v_pk_mul_f32 v[62:63], v[62:63], s[76:77]
	v_pk_mul_f32 v[56:57], v[56:57], s[76:77]
	v_pk_mul_f32 v[58:59], v[58:59], s[76:77]
	v_exp_f32_e32 v59, v59
	v_exp_f32_e32 v60, v60
	v_exp_f32_e32 v61, v61
	v_exp_f32_e32 v62, v62
	v_exp_f32_e32 v63, v63
	v_exp_f32_e32 v56, v56
	v_exp_f32_e32 v57, v57
	v_exp_f32_e32 v58, v58
	v_pk_add_f32 v[60:61], v[60:61], s[86:87]
	v_pk_add_f32 v[62:63], v[62:63], s[86:87]
	v_pk_add_f32 v[56:57], v[56:57], s[86:87]
	v_pk_add_f32 v[58:59], v[58:59], s[86:87]
	v_rcp_f32_e32 v59, v59
	v_rcp_f32_e32 v60, v60
	v_rcp_f32_e32 v61, v61
	v_rcp_f32_e32 v62, v62
	v_rcp_f32_e32 v63, v63
	v_rcp_f32_e32 v56, v56
	v_rcp_f32_e32 v57, v57
	v_rcp_f32_e32 v58, v58
	v_pk_mul_f32 v[52:53], v[52:53], v[60:61]
	v_pk_mul_f32 v[54:55], v[54:55], v[62:63]
	v_pk_mul_f32 v[48:49], v[48:49], v[56:57]
	v_pk_mul_f32 v[50:51], v[50:51], v[58:59]
	v_cvt_pk_bf16_f32 v56, v52, v53
	v_cvt_pk_bf16_f32 v57, v54, v55
	v_cvt_pk_bf16_f32 v58, v48, v49
	v_cvt_pk_bf16_f32 v59, v50, v51
	global_store_dwordx4 v[66:67], v[56:59], off
	s_nop 0
	s_nop 0
	v_add_u32_e32 v49, 0x90, v160
	v_mad_i64_i32 v[50:51], s[0:1], v49, s67, v[164:165]
	v_lshl_add_u64 v[50:51], v[50:51], 0, v[166:167]
	v_fmamk_f32 v48, v186, 0x3a800000, v172
	v_rsq_f32_e32 v48, v48
	s_nop 0
	v_pk_fma_f32 v[42:43], v[42:43], v[48:49], v[138:139] op_sel_hi:[1,0,1]
	v_pk_fma_f32 v[34:35], v[34:35], v[48:49], v[130:131] op_sel_hi:[1,0,1]
	v_pk_fma_f32 v[46:47], v[46:47], v[48:49], v[142:143] op_sel_hi:[1,0,1]
	v_pk_fma_f32 v[44:45], v[44:45], v[48:49], v[140:141] op_sel_hi:[1,0,1]
	v_pk_fma_f32 v[40:41], v[40:41], v[48:49], v[136:137] op_sel_hi:[1,0,1]
	v_pk_fma_f32 v[38:39], v[38:39], v[48:49], v[134:135] op_sel_hi:[1,0,1]
	v_pk_fma_f32 v[36:37], v[36:37], v[48:49], v[132:133] op_sel_hi:[1,0,1]
	v_pk_fma_f32 v[32:33], v[32:33], v[48:49], v[128:129] op_sel_hi:[1,0,1]
	v_pk_mul_f32 v[36:37], v[44:45], v[36:37]
	v_pk_mul_f32 v[38:39], v[46:47], v[38:39]
	v_pk_mul_f32 v[32:33], v[40:41], v[32:33]
	v_pk_mul_f32 v[34:35], v[42:43], v[34:35]
	v_pk_mul_f32 v[44:45], v[44:45], s[76:77]
	v_pk_mul_f32 v[46:47], v[46:47], s[76:77]
	v_pk_mul_f32 v[40:41], v[40:41], s[76:77]
	v_pk_mul_f32 v[42:43], v[42:43], s[76:77]
	v_exp_f32_e32 v43, v43
	v_exp_f32_e32 v44, v44
	v_exp_f32_e32 v45, v45
	v_exp_f32_e32 v46, v46
	v_exp_f32_e32 v47, v47
	v_exp_f32_e32 v40, v40
	v_exp_f32_e32 v41, v41
	v_exp_f32_e32 v42, v42
	v_pk_add_f32 v[44:45], v[44:45], s[86:87]
	v_pk_add_f32 v[46:47], v[46:47], s[86:87]
	v_pk_add_f32 v[40:41], v[40:41], s[86:87]
	v_pk_add_f32 v[42:43], v[42:43], s[86:87]
	v_rcp_f32_e32 v43, v43
	v_rcp_f32_e32 v44, v44
	v_rcp_f32_e32 v45, v45
	v_rcp_f32_e32 v46, v46
	v_rcp_f32_e32 v47, v47
	v_rcp_f32_e32 v40, v40
	v_rcp_f32_e32 v41, v41
	v_rcp_f32_e32 v42, v42
	v_pk_mul_f32 v[36:37], v[36:37], v[44:45]
	v_pk_mul_f32 v[38:39], v[38:39], v[46:47]
	v_pk_mul_f32 v[32:33], v[32:33], v[40:41]
	v_pk_mul_f32 v[34:35], v[34:35], v[42:43]
	v_cvt_pk_bf16_f32 v40, v36, v37
	v_cvt_pk_bf16_f32 v41, v38, v39
	v_cvt_pk_bf16_f32 v42, v32, v33
	v_cvt_pk_bf16_f32 v43, v34, v35
	global_store_dwordx4 v[50:51], v[40:43], off
	s_nop 0
	s_nop 0
	v_add_u32_e32 v33, 0xa0, v160
	v_mad_i64_i32 v[34:35], s[0:1], v33, s67, v[164:165]
	v_lshl_add_u64 v[34:35], v[34:35], 0, v[166:167]
	v_fmamk_f32 v32, v187, 0x3a800000, v172
	v_rsq_f32_e32 v32, v32
	s_nop 0
	v_pk_fma_f32 v[26:27], v[26:27], v[32:33], v[138:139] op_sel_hi:[1,0,1]
	v_pk_fma_f32 v[18:19], v[18:19], v[32:33], v[130:131] op_sel_hi:[1,0,1]
	v_pk_fma_f32 v[30:31], v[30:31], v[32:33], v[142:143] op_sel_hi:[1,0,1]
	v_pk_fma_f32 v[28:29], v[28:29], v[32:33], v[140:141] op_sel_hi:[1,0,1]
; __device__ __forceinline__ unsigned cvt_pk_bf16(float lo, float hi) { unsigned r; asm volatile("v_cvt_pk_bf16_f32 %0, %1, %2" : "=v"(r) : "v"(lo), "v"(hi)); return r; }
;     __device__ __forceinline__ static float sg(float g, float u) { return g * u * __builtin_amdgcn_rcpf(1.0f + __builtin_amdgcn_exp2f(-1.4426950408889634f * g)); }
;     __device__ __forceinline__ void operator()(const f32x4 (&acc)[2][2][4][2], const Unit& u, int wr, int wc, int fr, int fq) const {
;     ...
;             for (int m = 0; m < 4; ++m) { const int row = row0 + ai * HALF + m * 16;
;                 const float rstd = __builtin_amdgcn_rsqf(SS[row] * (1.0f / 1024.0f) + 1e-6f);
;                 const f32x4 g0 = acc[ai][0][m][0] * rstd + bv[0][0], g1 = acc[ai][0][m][1] * rstd + bv[0][1], u0 = acc[ai][1][m][0] * rstd + bv[1][0], u1 = acc[ai][1][m][1] * rstd + bv[1][1];
;                 u32x4 w; w.x = cvt_pk_bf16(sg(g0[0], u0[0]), sg(g0[1], u0[1])); w.y = cvt_pk_bf16(sg(g0[2], u0[2]), sg(g0[3], u0[3]));
;                 w.z = cvt_pk_bf16(sg(g1[0], u1[0]), sg(g1[1], u1[1])); w.w = cvt_pk_bf16(sg(g1[2], u1[2]), sg(g1[3], u1[3]));
;                 *(u32x4*)(O + (size_t)row * ldc + j0) = w; }
	v_pk_fma_f32 v[24:25], v[24:25], v[32:33], v[136:137] op_sel_hi:[1,0,1]
	v_pk_fma_f32 v[22:23], v[22:23], v[32:33], v[134:135] op_sel_hi:[1,0,1]
	v_pk_fma_f32 v[20:21], v[20:21], v[32:33], v[132:133] op_sel_hi:[1,0,1]
	v_pk_fma_f32 v[16:17], v[16:17], v[32:33], v[128:129] op_sel_hi:[1,0,1]
	v_pk_mul_f32 v[20:21], v[28:29], v[20:21]
	v_pk_mul_f32 v[22:23], v[30:31], v[22:23]
	v_pk_mul_f32 v[16:17], v[24:25], v[16:17]
	v_pk_mul_f32 v[18:19], v[26:27], v[18:19]
	v_pk_mul_f32 v[28:29], v[28:29], s[76:77]
	v_pk_mul_f32 v[30:31], v[30:31], s[76:77]
	v_pk_mul_f32 v[24:25], v[24:25], s[76:77]
	v_pk_mul_f32 v[26:27], v[26:27], s[76:77]
	v_exp_f32_e32 v27, v27
	v_exp_f32_e32 v28, v28
	v_exp_f32_e32 v29, v29
	v_exp_f32_e32 v30, v30
	v_exp_f32_e32 v31, v31
	v_exp_f32_e32 v24, v24
	v_exp_f32_e32 v25, v25
	v_exp_f32_e32 v26, v26
	v_pk_add_f32 v[28:29], v[28:29], s[86:87]
	v_pk_add_f32 v[30:31], v[30:31], s[86:87]
	v_pk_add_f32 v[24:25], v[24:25], s[86:87]
	v_pk_add_f32 v[26:27], v[26:27], s[86:87]
	v_rcp_f32_e32 v27, v27
	v_rcp_f32_e32 v28, v28
	v_rcp_f32_e32 v29, v29
	v_rcp_f32_e32 v30, v30
	v_rcp_f32_e32 v31, v31
	v_rcp_f32_e32 v24, v24
	v_rcp_f32_e32 v25, v25
	v_rcp_f32_e32 v26, v26
	v_pk_mul_f32 v[20:21], v[20:21], v[28:29]
	v_pk_mul_f32 v[22:23], v[22:23], v[30:31]
	v_pk_mul_f32 v[16:17], v[16:17], v[24:25]
	v_pk_mul_f32 v[18:19], v[18:19], v[26:27]
	v_cvt_pk_bf16_f32 v24, v20, v21
	v_cvt_pk_bf16_f32 v25, v22, v23
	v_cvt_pk_bf16_f32 v26, v16, v17
	v_cvt_pk_bf16_f32 v27, v18, v19
	global_store_dwordx4 v[34:35], v[24:27], off
	s_nop 0
	s_nop 0
	v_add_u32_e32 v17, 0xb0, v160
	v_mad_i64_i32 v[18:19], s[0:1], v17, s67, v[164:165]
	v_lshl_add_u64 v[18:19], v[18:19], 0, v[166:167]
	v_fmamk_f32 v16, v188, 0x3a800000, v172
	v_rsq_f32_e32 v16, v16
	s_nop 0
	v_pk_fma_f32 v[10:11], v[10:11], v[16:17], v[138:139] op_sel_hi:[1,0,1]
	v_pk_fma_f32 v[2:3], v[2:3], v[16:17], v[130:131] op_sel_hi:[1,0,1]
	v_pk_fma_f32 v[14:15], v[14:15], v[16:17], v[142:143] op_sel_hi:[1,0,1]
	v_pk_fma_f32 v[12:13], v[12:13], v[16:17], v[140:141] op_sel_hi:[1,0,1]
	v_pk_fma_f32 v[8:9], v[8:9], v[16:17], v[136:137] op_sel_hi:[1,0,1]
	v_pk_fma_f32 v[6:7], v[6:7], v[16:17], v[134:135] op_sel_hi:[1,0,1]
	v_pk_fma_f32 v[4:5], v[4:5], v[16:17], v[132:133] op_sel_hi:[1,0,1]
	v_pk_fma_f32 v[0:1], v[0:1], v[16:17], v[128:129] op_sel_hi:[1,0,1]
	v_pk_mul_f32 v[4:5], v[12:13], v[4:5]
	v_pk_mul_f32 v[6:7], v[14:15], v[6:7]
	v_pk_mul_f32 v[0:1], v[8:9], v[0:1]
	v_pk_mul_f32 v[2:3], v[10:11], v[2:3]
	v_pk_mul_f32 v[12:13], v[12:13], s[76:77]
	v_pk_mul_f32 v[14:15], v[14:15], s[76:77]
	v_pk_mul_f32 v[8:9], v[8:9], s[76:77]
	v_pk_mul_f32 v[10:11], v[10:11], s[76:77]
	v_exp_f32_e32 v11, v11
	v_exp_f32_e32 v12, v12
	v_exp_f32_e32 v13, v13
	v_exp_f32_e32 v14, v14
	v_exp_f32_e32 v15, v15
	v_exp_f32_e32 v8, v8
	v_exp_f32_e32 v9, v9
	v_exp_f32_e32 v10, v10
	v_pk_add_f32 v[12:13], v[12:13], s[86:87]
	v_pk_add_f32 v[14:15], v[14:15], s[86:87]
	v_pk_add_f32 v[8:9], v[8:9], s[86:87]
	v_pk_add_f32 v[10:11], v[10:11], s[86:87]
	v_rcp_f32_e32 v11, v11
	v_rcp_f32_e32 v12, v12
	v_rcp_f32_e32 v13, v13
	v_rcp_f32_e32 v14, v14
	v_rcp_f32_e32 v15, v15
	v_rcp_f32_e32 v8, v8
	v_rcp_f32_e32 v9, v9
	v_rcp_f32_e32 v10, v10
	v_pk_mul_f32 v[4:5], v[4:5], v[12:13]
	v_pk_mul_f32 v[6:7], v[6:7], v[14:15]
	v_pk_mul_f32 v[0:1], v[0:1], v[8:9]
	v_pk_mul_f32 v[2:3], v[2:3], v[10:11]
	v_cvt_pk_bf16_f32 v8, v4, v5
	v_cvt_pk_bf16_f32 v9, v6, v7
	v_cvt_pk_bf16_f32 v10, v0, v1
	v_cvt_pk_bf16_f32 v11, v2, v3
	global_store_dwordx4 v[18:19], v[8:11], off
	s_cbranch_vccnz .LBB0_792
	s_andn2_b64 vcc, exec, s[40:41]
	s_cbranch_vccnz .LBB0_791
	s_barrier
	s_branch .LBB0_791

; #define LAS __attribute__((address_space(3)))
; #define MAX3F(a, b, c) __builtin_fmaxf(__builtin_fmaxf((a), (b)), (c))
; #define MFMA32(a, b, c) __builtin_amdgcn_mfma_f32_32x32x16_bf16((a), (b), (c), 0, 0, 0)
; #define ATT_LOADK(t) do { kst[0] = *(const u32x4*)((const char*)KAp + (size_t)(t) * (size_t)(128 * ldka) + offA); \
;     if (HASB) { if (tid < 256) kst[KPT - 1] = *(const u32x4*)((const char*)KBp + (size_t)(t) * (size_t)(128 * ldkb) + offB); } } while (0)
; template <int DQK, int DKA, int DV> ...
;     ...
;         if (t + 3 < NT) ATT_STOREK((t + 3) & 3);
;         if (t + 2 < NT) ATT_STOREV((t + 2) & 3);
;         if (t + 4 < NT) ATT_LOADK(t + 4);
;         if (t + 3 < NT) ATT_LOADV(t + 3);
;         if (64 * t <= qlast) {
;             f32x16 p0, p1; s16x4 vlo[8], vhi[8]; bf16x8 pf[4];
;             LAS const unsigned char* vb = lds + C::VOFF + (t & 3) * C::VBYTES + voff;
;             __builtin_amdgcn_sched_barrier(0);
;             __builtin_amdgcn_s_setprio(3);
; #pragma unroll
;             for (int d0 = 0; d0 < ND; ++d0) {
;                 if (d0 == 0) { p0 = MFMA32(kf[0], qr[0], negm); p1 = MFMA32(kf[1], qr[0], negm); }
;                 else { p0 = MFMA32(kf[2 * d0], qr[d0], p0); p1 = MFMA32(kf[2 * d0 + 1], qr[d0], p1); }
;             }
;             __builtin_amdgcn_s_setprio(0);
;             __builtin_amdgcn_sched_barrier(0);
;             ATT_VFRAG(0);
;             __builtin_amdgcn_sched_barrier(0);
;             if (64 * t + 63 > q0 + 32 * wid) {
;                 const int kvb = 64 * t + 4 * hi;
; #pragma unroll
;                 for (int i = 0; i < 16; ++i) { const int kv = kvb + (i & 3) + 8 * (i >> 2); if (kv > qabs) p0[i] = -INFINITY; if (kv + 32 > qabs) p1[i] = -INFINITY; }
;             }
;             float mxa = MAX3F(p0[0], p0[1], p1[0]), mxb = MAX3F(p0[2], p0[3], p1[1]); mxa = MAX3F(mxa, p1[2], p1[3]);
; #pragma unroll
;             for (int i = 4; i < 16; i += 4) { mxa = MAX3F(mxa, p0[i], p0[i + 1]); mxb = MAX3F(mxb, p0[i + 2], p0[i + 3]); mxa = MAX3F(mxa, p1[i], p1[i + 1]); mxb = MAX3F(mxb, p1[i + 2], p1[i + 3]); }
;             float mx = fmaxf(mxa, mxb);
;             { auto rr = __builtin_amdgcn_permlane32_swap(__float_as_uint(mx), __float_as_uint(mx), false, false); mx = fmaxf(__uint_as_float(rr[0]), __uint_as_float(rr[1])); }
.Lfast_d:
	s_add_i32 s50, s1, -4
	s_and_b32 s22, s50, 3
	s_mulk_i32 s22, 0x5000
	v_add_u32_e32 v210, s22, v229
	s_add_i32 s51, s1, -3
	s_and_b32 s22, s51, 3
	s_mul_i32 s23, s22, 0x5000
	s_mulk_i32 s22, 0x2400
	v_add_u32_e32 v249, s22, v226
	v_add_u32_e32 v252, s23, v229
	s_setprio 3
	v_mfma_f32_32x32x16_bf16 v[80:95], v[144:147], v[112:115], v[0:15]
	ds_read_b128 v[144:147], v249
	v_mfma_f32_32x32x16_bf16 v[96:111], v[152:155], v[112:115], v[0:15]
	ds_read_b128 v[152:155], v249 offset:4608
	v_mfma_f32_32x32x16_bf16 v[80:95], v[140:143], v[116:119], v[80:95]
	ds_read_b128 v[140:143], v249 offset:32
	v_mfma_f32_32x32x16_bf16 v[96:111], v[148:151], v[116:119], v[96:111]
	ds_read_b128 v[148:151], v249 offset:4640
	v_mfma_f32_32x32x16_bf16 v[80:95], v[156:159], v[120:123], v[80:95]
	ds_read_b128 v[156:159], v249 offset:64
	v_mfma_f32_32x32x16_bf16 v[96:111], v[168:171], v[120:123], v[96:111]
	ds_read_b128 v[168:171], v249 offset:4672
	v_mfma_f32_32x32x16_bf16 v[80:95], v[160:163], v[124:127], v[80:95]
	ds_read_b128 v[160:163], v249 offset:96
	v_mfma_f32_32x32x16_bf16 v[96:111], v[164:167], v[124:127], v[96:111]
	ds_read_b128 v[164:167], v249 offset:4704
	s_setprio 0
	s_add_i32 s80, s1, -1
	s_add_i32 s23, s1, -2
	s_and_b32 s22, s80, 3
	s_mulk_i32 s22, 0x2400
	v_add_u32_e32 v253, s22, v217
	s_waitcnt vmcnt(0)
	ds_write_b128 v253, v[128:131]
	s_and_b32 s22, s23, 3
	s_mulk_i32 s22, 0x5000
	v_add_u32_e32 v253, s22, v227
	ds_write_b128 v253, v[132:135] offset:36864
	ds_write_b128 v253, v[136:139] offset:47104
	global_load_dwordx4 v[128:131], v[218:219], off
	v_add_co_u32_e32 v254, vcc, 0x2000, v220
	s_nop 1
	v_addc_co_u32_e32 v255, vcc, 0, v221, vcc
	global_load_dwordx4 v[132:135], v[220:221], off
	global_load_dwordx4 v[136:139], v[254:255], off
	v_max_f32_e32 v232, v81, v81
	v_max_f32_e32 v233, v80, v80
	v_max_f32_e32 v232, v233, v232
	v_max3_f32 v233, v82, v83, v97
	v_max3_f32 v232, v232, v96, v98
	v_max3_f32 v232, v232, v99, v84
	v_max3_f32 v233, v233, v86, v87
	v_max3_f32 v232, v232, v85, v100
	v_max3_f32 v233, v233, v102, v103
	v_max3_f32 v232, v232, v101, v88
	v_max3_f32 v233, v233, v90, v91
	v_max3_f32 v232, v232, v89, v104
	v_max3_f32 v233, v233, v106, v107
	v_max3_f32 v232, v232, v105, v92
	v_max3_f32 v233, v233, v94, v95
	v_max3_f32 v232, v232, v93, v108
	v_max3_f32 v233, v233, v110, v111
	v_max3_f32 v232, v232, v109, v233
	v_mov_b32_e32 v233, v232
	s_nop 1
	v_permlane32_swap_b32_e32 v232, v233
	v_max_f32_e32 v233, v233, v233
	v_max_f32_e32 v232, v232, v232
	v_max_f32_e32 v232, v232, v233
	v_cmp_lt_f32_e32 vcc, s62, v232
	s_cbranch_vccnz .Lfast_d_bail1
	s_waitcnt lgkmcnt(0)
	v_exp_f32_e32 v80, v80
	v_exp_f32_e32 v96, v96
	v_exp_f32_e32 v81, v81
	v_exp_f32_e32 v97, v97
	v_mfma_f32_32x32x16_bf16 v[172:187], v[144:147], v[112:115], v[0:15]
	ds_read_b64_tr_b16 v[144:145], v210 offset:36864
	ds_read_b64_tr_b16 v[146:147], v210 offset:39424
	v_exp_f32_e32 v82, v82
	v_exp_f32_e32 v98, v98
	v_exp_f32_e32 v83, v83
	v_exp_f32_e32 v99, v99
	v_mfma_f32_32x32x16_bf16 v[188:203], v[152:155], v[112:115], v[0:15]
	ds_read_b64_tr_b16 v[152:153], v210 offset:36928
	ds_read_b64_tr_b16 v[154:155], v210 offset:39488
	v_exp_f32_e32 v84, v84
	v_exp_f32_e32 v100, v100
	v_exp_f32_e32 v85, v85
	v_exp_f32_e32 v101, v101
	v_mfma_f32_32x32x16_bf16 v[172:187], v[140:143], v[116:119], v[172:187]
	ds_read_b64_tr_b16 v[140:141], v210 offset:41984
	ds_read_b64_tr_b16 v[142:143], v210 offset:44544
	v_exp_f32_e32 v86, v86
	v_exp_f32_e32 v102, v102
	v_exp_f32_e32 v87, v87
	v_exp_f32_e32 v103, v103
	v_mfma_f32_32x32x16_bf16 v[188:203], v[148:151], v[116:119], v[188:203]
	ds_read_b64_tr_b16 v[148:149], v210 offset:42048
	ds_read_b64_tr_b16 v[150:151], v210 offset:44608
	v_exp_f32_e32 v88, v88
	v_exp_f32_e32 v104, v104
	v_exp_f32_e32 v89, v89
	v_exp_f32_e32 v105, v105
	v_mfma_f32_32x32x16_bf16 v[172:187], v[156:159], v[120:123], v[172:187]
	ds_read_b64_tr_b16 v[156:157], v210 offset:47104
	ds_read_b64_tr_b16 v[158:159], v210 offset:49664
	v_exp_f32_e32 v90, v90
	v_exp_f32_e32 v106, v106
	v_exp_f32_e32 v91, v91
	v_exp_f32_e32 v107, v107
	v_mfma_f32_32x32x16_bf16 v[188:203], v[168:171], v[120:123], v[188:203]
	ds_read_b64_tr_b16 v[168:169], v210 offset:47168
	ds_read_b64_tr_b16 v[170:171], v210 offset:49728
	v_exp_f32_e32 v92, v92
	v_exp_f32_e32 v108, v108
	v_exp_f32_e32 v93, v93
	v_exp_f32_e32 v109, v109
	v_mfma_f32_32x32x16_bf16 v[172:187], v[160:163], v[124:127], v[172:187]
	ds_read_b64_tr_b16 v[160:161], v210 offset:52224
	ds_read_b64_tr_b16 v[162:163], v210 offset:54784
	v_exp_f32_e32 v94, v94
	v_exp_f32_e32 v110, v110
	v_exp_f32_e32 v95, v95
	v_exp_f32_e32 v111, v111
	v_mfma_f32_32x32x16_bf16 v[188:203], v[164:167], v[124:127], v[188:203]
	ds_read_b64_tr_b16 v[164:165], v210 offset:52288
	ds_read_b64_tr_b16 v[166:167], v210 offset:54848
	v_cvt_pk_bf16_f32 v232, v80, v81
	v_cvt_pk_bf16_f32 v233, v82, v83
	v_cvt_pk_bf16_f32 v234, v84, v85
	v_cvt_pk_bf16_f32 v235, v86, v87
	v_cvt_pk_bf16_f32 v236, v96, v97
	v_cvt_pk_bf16_f32 v237, v98, v99
	v_cvt_pk_bf16_f32 v238, v100, v101
	v_cvt_pk_bf16_f32 v239, v102, v103
	v_cvt_pk_bf16_f32 v240, v88, v89
	v_cvt_pk_bf16_f32 v241, v90, v91
	v_cvt_pk_bf16_f32 v242, v92, v93
	v_cvt_pk_bf16_f32 v243, v94, v95
	v_cvt_pk_bf16_f32 v244, v104, v105
	v_cvt_pk_bf16_f32 v245, v106, v107
	v_cvt_pk_bf16_f32 v246, v108, v109
	v_cvt_pk_bf16_f32 v247, v110, v111
	v_max_f32_e32 v250, v173, v173
	v_max_f32_e32 v251, v172, v172
	v_max_f32_e32 v250, v251, v250
	v_max3_f32 v251, v174, v175, v189
	v_max3_f32 v250, v250, v188, v190
	v_max3_f32 v250, v250, v191, v176
	v_max3_f32 v251, v251, v178, v179
	v_max3_f32 v250, v250, v177, v192
	v_max3_f32 v251, v251, v194, v195
	v_max3_f32 v250, v250, v193, v180
	v_max3_f32 v251, v251, v182, v183
	v_max3_f32 v250, v250, v181, v196
	v_max3_f32 v251, v251, v198, v199
	v_max3_f32 v250, v250, v197, v184
	v_max3_f32 v251, v251, v186, v187
	v_max3_f32 v250, v250, v185, v200
	v_max3_f32 v251, v251, v202, v203
	v_max3_f32 v250, v250, v201, v251
	v_mov_b32_e32 v251, v250
	s_nop 1
	v_permlane32_swap_b32_e32 v250, v251
	v_max_f32_e32 v251, v251, v251
	v_max_f32_e32 v250, v250, v250
	v_max_f32_e32 v250, v250, v251
	v_cmp_lt_f32_e32 vcc, s62, v250
	s_cbranch_vccnz .Lfast_d_bail2
; __device__ __forceinline__ unsigned cvtpk_s(float lo, float hi) { f32x2_t v = {lo, hi}; bf16x2_t b = __builtin_convertvector(v, bf16x2_t); return __builtin_bit_cast(unsigned, b); }
; #define ATT_LOADK(t) do { kst[0] = *(const u32x4*)((const char*)KAp + (size_t)(t) * (size_t)(128 * ldka) + offA); \
;     if (HASB) { if (tid < 256) kst[KPT - 1] = *(const u32x4*)((const char*)KBp + (size_t)(t) * (size_t)(128 * ldkb) + offB); } } while (0)
; template <int DQK, int DKA, int DV> ...
;     ...
;         if (t + 3 < NT) ATT_STOREK((t + 3) & 3);
;         if (t + 2 < NT) ATT_STOREV((t + 2) & 3);
;         if (t + 4 < NT) ATT_LOADK(t + 4);
;         if (t + 3 < NT) ATT_LOADV(t + 3);
;     ...
;             { float rs = 0.f;
; #pragma unroll
;               for (int i = 0; i < 16; ++i) { p0[i] = __builtin_amdgcn_exp2f(NEGM ? p0[i] : p0[i] - m); p1[i] = __builtin_amdgcn_exp2f(NEGM ? p1[i] : p1[i] - m); rs += p0[i] + p1[i]; }
;               l += rs;
; #pragma unroll
;               for (int s = 0; s < 2; ++s) { u32x4 w0, w1;
;                 w0.x = cvtpk_s(p0[8 * s], p0[8 * s + 1]); w0.y = cvtpk_s(p0[8 * s + 2], p0[8 * s + 3]); w0.z = cvtpk_s(p0[8 * s + 4], p0[8 * s + 5]); w0.w = cvtpk_s(p0[8 * s + 6], p0[8 * s + 7]);
;                 w1.x = cvtpk_s(p1[8 * s], p1[8 * s + 1]); w1.y = cvtpk_s(p1[8 * s + 2], p1[8 * s + 3]); w1.z = cvtpk_s(p1[8 * s + 4], p1[8 * s + 5]); w1.w = cvtpk_s(p1[8 * s + 6], p1[8 * s + 7]);
;                 pf[s] = __builtin_bit_cast(bf16x8, w0); pf[2 + s] = __builtin_bit_cast(bf16x8, w1); } }
;             __builtin_amdgcn_sched_barrier(0);
;             if (NV == 2) {
;                 __builtin_amdgcn_s_setprio(3); ATT_PV(0); __builtin_amdgcn_s_setprio(0);
;                 __builtin_amdgcn_sched_barrier(0);
;                 if (t + 1 < NT) ATT_KFRAG(ks1);
;             } else {
;                 __builtin_amdgcn_s_setprio(3); ATT_PV(0); __builtin_amdgcn_s_setprio(0);
;                 __builtin_amdgcn_sched_barrier(0);
;                 ATT_VFRAG(2);
;                 __builtin_amdgcn_sched_barrier(0);
;                 __builtin_amdgcn_s_setprio(3); ATT_PV(2); __builtin_amdgcn_s_setprio(0);
;                 __builtin_amdgcn_sched_barrier(0);
;                 if (t + 1 < NT) ATT_KFRAG(ks1);
;             }
	s_setprio 0
	s_waitcnt lgkmcnt(0)
	v_mfma_f32_32x32x16_bf16 v[32:47], v[144:147], v[232:235], v[32:47]
	v_lshl_add_u64 v[218:219], v[218:219], 0, s[10:11]
	v_lshl_add_u64 v[220:221], v[220:221], 0, s[8:9]
	s_add_i32 s23, s1, -1
	s_and_b32 s22, s1, 3
	s_mulk_i32 s22, 0x2400
	v_add_u32_e32 v253, s22, v217
	s_waitcnt vmcnt(0)
	ds_write_b128 v253, v[128:131]
	s_and_b32 s22, s23, 3
	s_mulk_i32 s22, 0x5000
	v_mfma_f32_32x32x16_bf16 v[16:31], v[152:155], v[232:235], v[16:31]
	v_add_u32_e32 v253, s22, v227
	ds_write_b128 v253, v[132:135] offset:36864
	ds_write_b128 v253, v[136:139] offset:47104
	global_load_dwordx4 v[128:131], v[218:219], off
	v_add_co_u32_e32 v254, vcc, 0x2000, v220
	s_nop 1
	v_addc_co_u32_e32 v255, vcc, 0, v221, vcc
	global_load_dwordx4 v[132:135], v[220:221], off
	global_load_dwordx4 v[136:139], v[254:255], off
	v_add_f32_e32 v80, v80, v96
	v_add_f32_e32 v81, v81, v97
	v_add_f32_e32 v80, 0, v80
	v_add_f32_e32 v82, v82, v98
	v_mfma_f32_32x32x16_bf16 v[32:47], v[140:143], v[240:243], v[32:47]
	v_add_f32_e32 v80, v81, v80
	v_add_f32_e32 v83, v83, v99
	v_add_f32_e32 v80, v82, v80
	v_add_f32_e32 v84, v84, v100
	v_add_f32_e32 v80, v83, v80
	v_add_f32_e32 v85, v85, v101
	v_add_f32_e32 v80, v84, v80
	v_add_f32_e32 v86, v86, v102
	v_add_f32_e32 v80, v85, v80
	v_add_f32_e32 v87, v87, v103
	v_mfma_f32_32x32x16_bf16 v[16:31], v[148:151], v[240:243], v[16:31]
	v_add_f32_e32 v80, v86, v80
	v_add_f32_e32 v88, v88, v104
	v_add_f32_e32 v80, v87, v80
	v_add_f32_e32 v89, v89, v105
	v_add_f32_e32 v80, v88, v80
	v_add_f32_e32 v90, v90, v106
	v_add_f32_e32 v80, v89, v80
	v_add_f32_e32 v91, v91, v107
	v_add_f32_e32 v80, v90, v80
	v_add_f32_e32 v92, v92, v108
	v_mfma_f32_32x32x16_bf16 v[32:47], v[156:159], v[236:239], v[32:47]
	v_add_f32_e32 v80, v91, v80
	v_add_f32_e32 v93, v93, v109
	v_add_f32_e32 v80, v92, v80
	v_add_f32_e32 v94, v94, v110
	v_add_f32_e32 v80, v93, v80
	v_add_f32_e32 v95, v95, v111
	v_add_f32_e32 v80, v94, v80
	v_add_f32_e32 v80, v95, v80
	v_add_f32_e32 v231, v231, v80
	ds_read_b64_tr_b16 v[80:81], v210 offset:36992
	ds_read_b64_tr_b16 v[82:83], v210 offset:39552
	ds_read_b64_tr_b16 v[84:85], v210 offset:37056
	ds_read_b64_tr_b16 v[86:87], v210 offset:39616
	v_mfma_f32_32x32x16_bf16 v[16:31], v[168:171], v[236:239], v[16:31]
	ds_read_b64_tr_b16 v[88:89], v210 offset:42112
	ds_read_b64_tr_b16 v[90:91], v210 offset:44672
	ds_read_b64_tr_b16 v[92:93], v210 offset:42176
	ds_read_b64_tr_b16 v[94:95], v210 offset:44736
	ds_read_b64_tr_b16 v[96:97], v210 offset:47232
	ds_read_b64_tr_b16 v[98:99], v210 offset:49792
	ds_read_b64_tr_b16 v[100:101], v210 offset:47296
	ds_read_b64_tr_b16 v[102:103], v210 offset:49856
	v_mfma_f32_32x32x16_bf16 v[32:47], v[160:163], v[244:247], v[32:47]
	ds_read_b64_tr_b16 v[104:105], v210 offset:52352
	ds_read_b64_tr_b16 v[106:107], v210 offset:54912
	ds_read_b64_tr_b16 v[108:109], v210 offset:52416
	ds_read_b64_tr_b16 v[110:111], v210 offset:54976
	v_exp_f32_e32 v172, v172
	v_exp_f32_e32 v188, v188
	v_mfma_f32_32x32x16_bf16 v[16:31], v[164:167], v[244:247], v[16:31]
	v_exp_f32_e32 v173, v173
	v_exp_f32_e32 v189, v189
	v_exp_f32_e32 v174, v174
	v_exp_f32_e32 v190, v190
	s_waitcnt lgkmcnt(14)
	v_mfma_f32_32x32x16_bf16 v[64:79], v[80:83], v[232:235], v[64:79]
	ds_read_b64_tr_b16 v[144:145], v252 offset:36864
	ds_read_b64_tr_b16 v[146:147], v252 offset:39424
	v_exp_f32_e32 v175, v175
	v_exp_f32_e32 v191, v191
	v_exp_f32_e32 v176, v176
	v_exp_f32_e32 v192, v192
	s_waitcnt lgkmcnt(14)
	v_mfma_f32_32x32x16_bf16 v[48:63], v[84:87], v[232:235], v[48:63]
	ds_read_b64_tr_b16 v[152:153], v252 offset:36928
	ds_read_b64_tr_b16 v[154:155], v252 offset:39488
	v_exp_f32_e32 v177, v177
	v_exp_f32_e32 v193, v193
	v_exp_f32_e32 v178, v178
	v_exp_f32_e32 v194, v194
	s_waitcnt lgkmcnt(14)
	v_mfma_f32_32x32x16_bf16 v[64:79], v[88:91], v[240:243], v[64:79]
	ds_read_b64_tr_b16 v[140:141], v252 offset:41984
	ds_read_b64_tr_b16 v[142:143], v252 offset:44544
	v_exp_f32_e32 v179, v179
	v_exp_f32_e32 v195, v195
	v_exp_f32_e32 v180, v180
	s_waitcnt lgkmcnt(14)
	v_mfma_f32_32x32x16_bf16 v[48:63], v[92:95], v[240:243], v[48:63]
	ds_read_b64_tr_b16 v[148:149], v252 offset:42048
	ds_read_b64_tr_b16 v[150:151], v252 offset:44608
	v_exp_f32_e32 v196, v196
	v_exp_f32_e32 v181, v181
	v_exp_f32_e32 v197, v197
	s_waitcnt lgkmcnt(14)
	v_mfma_f32_32x32x16_bf16 v[64:79], v[96:99], v[236:239], v[64:79]
	ds_read_b64_tr_b16 v[156:157], v252 offset:47104
	ds_read_b64_tr_b16 v[158:159], v252 offset:49664
	v_exp_f32_e32 v182, v182
	v_exp_f32_e32 v198, v198
	v_exp_f32_e32 v183, v183
	s_waitcnt lgkmcnt(14)
	v_mfma_f32_32x32x16_bf16 v[48:63], v[100:103], v[236:239], v[48:63]
	ds_read_b64_tr_b16 v[168:169], v252 offset:47168
	ds_read_b64_tr_b16 v[170:171], v252 offset:49728
	v_exp_f32_e32 v199, v199
	v_exp_f32_e32 v184, v184
	v_exp_f32_e32 v200, v200
	s_waitcnt lgkmcnt(14)
; __device__ __forceinline__ unsigned cvtpk_s(float lo, float hi) { f32x2_t v = {lo, hi}; bf16x2_t b = __builtin_convertvector(v, bf16x2_t); return __builtin_bit_cast(unsigned, b); }
; #define ATT_KFRAG(slot) do { LAS const unsigned char* kb_ = lds + (slot) * C::KBYTES + koff; \
;     _Pragma("unroll") for (int d0 = 0; d0 < ND; ++d0) { kf[2 * d0] = *(LAS const bf16x8*)(kb_ + 32 * d0); kf[2 * d0 + 1] = *(LAS const bf16x8*)(kb_ + 32 * KP + 32 * d0); } } while (0)
; template <int DQK, int DKA, int DV> ...
;     ...
;             { float rs = 0.f;
; #pragma unroll
;               for (int i = 0; i < 16; ++i) { p0[i] = __builtin_amdgcn_exp2f(NEGM ? p0[i] : p0[i] - m); p1[i] = __builtin_amdgcn_exp2f(NEGM ? p1[i] : p1[i] - m); rs += p0[i] + p1[i]; }
;               l += rs;
; #pragma unroll
;               for (int s = 0; s < 2; ++s) { u32x4 w0, w1;
;                 w0.x = cvtpk_s(p0[8 * s], p0[8 * s + 1]); w0.y = cvtpk_s(p0[8 * s + 2], p0[8 * s + 3]); w0.z = cvtpk_s(p0[8 * s + 4], p0[8 * s + 5]); w0.w = cvtpk_s(p0[8 * s + 6], p0[8 * s + 7]);
;                 w1.x = cvtpk_s(p1[8 * s], p1[8 * s + 1]); w1.y = cvtpk_s(p1[8 * s + 2], p1[8 * s + 3]); w1.z = cvtpk_s(p1[8 * s + 4], p1[8 * s + 5]); w1.w = cvtpk_s(p1[8 * s + 6], p1[8 * s + 7]);
;                 pf[s] = __builtin_bit_cast(bf16x8, w0); pf[2 + s] = __builtin_bit_cast(bf16x8, w1); } }
;             __builtin_amdgcn_sched_barrier(0);
;             if (NV == 2) {
;                 __builtin_amdgcn_s_setprio(3); ATT_PV(0); __builtin_amdgcn_s_setprio(0);
;                 __builtin_amdgcn_sched_barrier(0);
;                 if (t + 1 < NT) ATT_KFRAG(ks1);
;             } else {
;                 __builtin_amdgcn_s_setprio(3); ATT_PV(0); __builtin_amdgcn_s_setprio(0);
;                 __builtin_amdgcn_sched_barrier(0);
;                 ATT_VFRAG(2);
;                 __builtin_amdgcn_sched_barrier(0);
;                 __builtin_amdgcn_s_setprio(3); ATT_PV(2); __builtin_amdgcn_s_setprio(0);
;                 __builtin_amdgcn_sched_barrier(0);
;                 if (t + 1 < NT) ATT_KFRAG(ks1);
;             }
;             __builtin_amdgcn_sched_barrier(0);
;         }
;         if (t & 1) asm volatile("s_waitcnt lgkmcnt(0)\n\ts_barrier" ::: "memory");
	v_mfma_f32_32x32x16_bf16 v[64:79], v[104:107], v[244:247], v[64:79]
	ds_read_b64_tr_b16 v[160:161], v252 offset:52224
	ds_read_b64_tr_b16 v[162:163], v252 offset:54784
	v_exp_f32_e32 v185, v185
	v_exp_f32_e32 v201, v201
	v_exp_f32_e32 v186, v186
	s_waitcnt lgkmcnt(14)
	v_mfma_f32_32x32x16_bf16 v[48:63], v[108:111], v[244:247], v[48:63]
	ds_read_b64_tr_b16 v[164:165], v252 offset:52288
	ds_read_b64_tr_b16 v[166:167], v252 offset:54848
	v_exp_f32_e32 v202, v202
	v_exp_f32_e32 v187, v187
	v_exp_f32_e32 v203, v203
	s_setprio 0
	v_cvt_pk_bf16_f32 v232, v172, v173
	v_cvt_pk_bf16_f32 v233, v174, v175
	v_cvt_pk_bf16_f32 v234, v176, v177
	v_cvt_pk_bf16_f32 v235, v178, v179
	v_cvt_pk_bf16_f32 v236, v188, v189
	v_cvt_pk_bf16_f32 v237, v190, v191
	v_cvt_pk_bf16_f32 v238, v192, v193
	v_cvt_pk_bf16_f32 v239, v194, v195
	v_cvt_pk_bf16_f32 v240, v180, v181
	v_cvt_pk_bf16_f32 v241, v182, v183
	v_cvt_pk_bf16_f32 v242, v184, v185
	v_cvt_pk_bf16_f32 v243, v186, v187
	v_cvt_pk_bf16_f32 v244, v196, v197
	v_cvt_pk_bf16_f32 v245, v198, v199
	v_cvt_pk_bf16_f32 v246, v200, v201
	v_cvt_pk_bf16_f32 v247, v202, v203
	v_add_f32_e32 v172, v172, v188
	v_add_f32_e32 v173, v173, v189
	v_add_f32_e32 v172, 0, v172
	v_add_f32_e32 v174, v174, v190
	v_add_f32_e32 v172, v173, v172
	v_add_f32_e32 v175, v175, v191
	v_add_f32_e32 v172, v174, v172
	v_add_f32_e32 v176, v176, v192
	v_add_f32_e32 v172, v175, v172
	v_add_f32_e32 v177, v177, v193
	v_add_f32_e32 v172, v176, v172
	v_add_f32_e32 v178, v178, v194
	s_waitcnt lgkmcnt(0)
	v_mfma_f32_32x32x16_bf16 v[32:47], v[144:147], v[232:235], v[32:47]
	ds_read_b64_tr_b16 v[80:81], v252 offset:36992
	ds_read_b64_tr_b16 v[82:83], v252 offset:39552
	ds_read_b64_tr_b16 v[84:85], v252 offset:37056
	ds_read_b64_tr_b16 v[86:87], v252 offset:39616
	v_add_f32_e32 v172, v177, v172
	v_add_f32_e32 v179, v179, v195
	v_add_f32_e32 v172, v178, v172
	v_mfma_f32_32x32x16_bf16 v[16:31], v[152:155], v[232:235], v[16:31]
	ds_read_b64_tr_b16 v[88:89], v252 offset:42112
	ds_read_b64_tr_b16 v[90:91], v252 offset:44672
	ds_read_b64_tr_b16 v[92:93], v252 offset:42176
	ds_read_b64_tr_b16 v[94:95], v252 offset:44736
	v_add_f32_e32 v180, v180, v196
	v_add_f32_e32 v172, v179, v172
	v_add_f32_e32 v181, v181, v197
	v_mfma_f32_32x32x16_bf16 v[32:47], v[140:143], v[240:243], v[32:47]
	ds_read_b64_tr_b16 v[96:97], v252 offset:47232
	ds_read_b64_tr_b16 v[98:99], v252 offset:49792
	ds_read_b64_tr_b16 v[100:101], v252 offset:47296
	ds_read_b64_tr_b16 v[102:103], v252 offset:49856
	v_add_f32_e32 v172, v180, v172
	v_add_f32_e32 v182, v182, v198
	v_add_f32_e32 v172, v181, v172
	v_mfma_f32_32x32x16_bf16 v[16:31], v[148:151], v[240:243], v[16:31]
	ds_read_b64_tr_b16 v[104:105], v252 offset:52352
	ds_read_b64_tr_b16 v[106:107], v252 offset:54912
	ds_read_b64_tr_b16 v[108:109], v252 offset:52416
	ds_read_b64_tr_b16 v[110:111], v252 offset:54976
	v_add_f32_e32 v183, v183, v199
	v_add_f32_e32 v172, v182, v172
	v_add_f32_e32 v184, v184, v200
	v_mfma_f32_32x32x16_bf16 v[32:47], v[156:159], v[236:239], v[32:47]
	v_add_f32_e32 v172, v183, v172
	v_add_f32_e32 v185, v185, v201
	v_add_f32_e32 v172, v184, v172
	v_mfma_f32_32x32x16_bf16 v[16:31], v[168:171], v[236:239], v[16:31]
	v_add_f32_e32 v186, v186, v202
	v_add_f32_e32 v172, v185, v172
	v_add_f32_e32 v187, v187, v203
	v_mfma_f32_32x32x16_bf16 v[32:47], v[160:163], v[244:247], v[32:47]
	v_add_f32_e32 v172, v186, v172
	v_add_f32_e32 v172, v187, v172
	v_add_f32_e32 v231, v231, v172
	v_mfma_f32_32x32x16_bf16 v[16:31], v[164:167], v[244:247], v[16:31]
	s_add_i32 s1, s1, 2
	s_addk_i32 s79, 0x80
	s_add_i32 s22, s1, -4
	s_and_b32 s22, s22, 3
	s_mulk_i32 s22, 0x2400
	v_add_u32_e32 v249, s22, v226
	s_waitcnt lgkmcnt(0)
	v_mfma_f32_32x32x16_bf16 v[64:79], v[80:83], v[232:235], v[64:79]
	ds_read_b128 v[144:147], v249
	ds_read_b128 v[152:155], v249 offset:4608
	v_mfma_f32_32x32x16_bf16 v[48:63], v[84:87], v[232:235], v[48:63]
	ds_read_b128 v[140:143], v249 offset:32
	ds_read_b128 v[148:151], v249 offset:4640
	v_mfma_f32_32x32x16_bf16 v[64:79], v[88:91], v[240:243], v[64:79]
	ds_read_b128 v[156:159], v249 offset:64
	ds_read_b128 v[168:171], v249 offset:4672
	v_mfma_f32_32x32x16_bf16 v[48:63], v[92:95], v[240:243], v[48:63]
	ds_read_b128 v[160:163], v249 offset:96
	ds_read_b128 v[164:167], v249 offset:4704
	v_mfma_f32_32x32x16_bf16 v[64:79], v[96:99], v[236:239], v[64:79]
	v_lshl_add_u64 v[218:219], v[218:219], 0, s[10:11]
	v_mfma_f32_32x32x16_bf16 v[48:63], v[100:103], v[236:239], v[48:63]
	v_lshl_add_u64 v[220:221], v[220:221], 0, s[8:9]
	v_mfma_f32_32x32x16_bf16 v[64:79], v[104:107], v[244:247], v[64:79]
	v_mfma_f32_32x32x16_bf16 v[48:63], v[108:111], v[244:247], v[48:63]
	s_setprio 0
	s_waitcnt lgkmcnt(0)
	s_barrier
	s_branch .LBB0_1124

; __device__ __forceinline__ unsigned cvt_pk_bf16(float lo, float hi) { unsigned r; asm volatile("v_cvt_pk_bf16_f32 %0, %1, %2" : "=v"(r) : "v"(lo), "v"(hi)); return r; }
;     __device__ __forceinline__ static float sg(float g, float u) { return g * u * __builtin_amdgcn_rcpf(1.0f + __builtin_amdgcn_exp2f(-1.4426950408889634f * g)); }
;     __device__ __forceinline__ void operator()(const f32x4 (&acc)[2][2][4][2], const Unit& u, int wr, int wc, int fr, int fq) const {
;         const int row0 = u.pm * BM + wr * 64 + fr, col0 = u.pn * BM + wc * 32 + 8 * fq, j0 = u.pn * HALF + wc * 32 + 8 * fq;
;         const float* bp = bt + (size_t)((u.pm * BM) >> 12) * (2 * 2816) + col0;
;         f32x4 bv[2][2];
; #pragma unroll
;         for (int bj = 0; bj < 2; ++bj)
; #pragma unroll
;             for (int n = 0; n < 2; ++n) bv[bj][n] = *(const f32x4*)(bp + bj * HALF + 4 * n);
; #pragma unroll
;         for (int ai = 0; ai < 2; ++ai)
; #pragma unroll
;             for (int m = 0; m < 4; ++m) { const int row = row0 + ai * HALF + m * 16;
;                 const float rstd = __builtin_amdgcn_rsqf(SS[row] * (1.0f / 1024.0f) + 1e-6f);
;                 const f32x4 g0 = acc[ai][0][m][0] * rstd + bv[0][0], g1 = acc[ai][0][m][1] * rstd + bv[0][1], u0 = acc[ai][1][m][0] * rstd + bv[1][0], u1 = acc[ai][1][m][1] * rstd + bv[1][1];
;                 u32x4 w; w.x = cvt_pk_bf16(sg(g0[0], u0[0]), sg(g0[1], u0[1])); w.y = cvt_pk_bf16(sg(g0[2], u0[2]), sg(g0[3], u0[3]));
;                 w.z = cvt_pk_bf16(sg(g1[0], u1[0]), sg(g1[1], u1[1])); w.w = cvt_pk_bf16(sg(g1[2], u1[2]), sg(g1[3], u1[3]));
;                 *(u32x4*)(O + (size_t)row * ldc + j0) = w; }
.LBB0_1312:
	s_lshl_b32 s0, s68, 8
	v_mov_b32_e32 v129, v204
	s_add_i32 s0, s0, s58
	s_lshl_b32 s1, s69, 8
	v_lshrrev_b32_e32 v128, 1, v129
	v_and_or_b32 v160, v129, 15, s0
	s_or_b32 s1, s1, s59
	v_and_b32_e32 v166, 24, v128
	v_ashrrev_i32_e32 v161, 31, v160
	v_or_b32_e32 v128, s1, v166
	s_lshl_b32 s1, s69, 7
	v_lshl_add_u64 v[162:163], v[160:161], 2, s[10:11]
	s_or_b32 s22, s1, s59
	s_ashr_i32 s1, s68, 4
	s_mov_b32 s76, 0xbfb8aa3b
	s_mov_b32 s77, 0xbfb8aa3b
	s_mov_b32 s86, 1.0
	s_mov_b32 s87, 1.0
	global_load_dword v161, v[162:163], off
	global_load_dword v182, v[162:163], off offset:64
	global_load_dword v183, v[162:163], off offset:128
	global_load_dword v184, v[162:163], off offset:192
	global_load_dword v185, v[162:163], off offset:512
	global_load_dword v186, v[162:163], off offset:576
	global_load_dword v187, v[162:163], off offset:640
	global_load_dword v188, v[162:163], off offset:704
	s_mul_hi_i32 s23, s1, 0x5800
	s_mulk_i32 s1, 0x5800
	s_add_u32 s0, s53, s1
	s_addc_u32 s1, s54, s23
	v_ashrrev_i32_e32 v129, 31, v128
	v_lshl_add_u64 v[128:129], v[128:129], 2, s[0:1]
	global_load_dwordx4 v[140:143], v[128:129], off
	global_load_dwordx4 v[136:139], v[128:129], off offset:16
	global_load_dwordx4 v[132:135], v[128:129], off offset:512
	s_nop 0
	global_load_dwordx4 v[128:131], v[128:129], off offset:528
	v_or_b32_e32 v166, s22, v166
	v_mov_b64_e32 v[164:165], s[20:21]
	v_ashrrev_i32_e32 v167, 31, v166
	v_mad_i64_i32 v[174:175], s[0:1], v160, s65, v[164:165]
	v_or_b32_e32 v176, 16, v160
	v_lshlrev_b64 v[166:167], 1, v[166:167]
	v_ashrrev_i32_e32 v177, 31, v176
	v_lshl_add_u64 v[174:175], v[174:175], 0, v[166:167]
	v_lshl_add_u64 v[180:181], v[176:177], 2, s[10:11]
	s_and_b64 vcc, exec, s[6:7]
	s_mov_b64 s[6:7], -1
	s_waitcnt vmcnt(0)
	v_fmamk_f32 v161, v161, 0x3a800000, v172
	v_rsq_f32_e32 v178, v161
	s_nop 0
	v_pk_fma_f32 v[126:127], v[126:127], v[178:179], v[138:139] op_sel_hi:[1,0,1]
	v_pk_fma_f32 v[122:123], v[122:123], v[178:179], v[142:143] op_sel_hi:[1,0,1]
	v_pk_fma_f32 v[114:115], v[114:115], v[178:179], v[130:131] op_sel_hi:[1,0,1]
	v_pk_fma_f32 v[120:121], v[120:121], v[178:179], v[140:141] op_sel_hi:[1,0,1]
	v_pk_fma_f32 v[124:125], v[124:125], v[178:179], v[136:137] op_sel_hi:[1,0,1]
	v_pk_fma_f32 v[118:119], v[118:119], v[178:179], v[134:135] op_sel_hi:[1,0,1]
	v_pk_fma_f32 v[116:117], v[116:117], v[178:179], v[132:133] op_sel_hi:[1,0,1]
	v_pk_fma_f32 v[112:113], v[112:113], v[178:179], v[128:129] op_sel_hi:[1,0,1]
	v_pk_mul_f32 v[116:117], v[120:121], v[116:117]
	v_pk_mul_f32 v[118:119], v[122:123], v[118:119]
	v_pk_mul_f32 v[112:113], v[124:125], v[112:113]
	v_pk_mul_f32 v[114:115], v[126:127], v[114:115]
	v_pk_mul_f32 v[120:121], v[120:121], s[76:77]
	v_pk_mul_f32 v[122:123], v[122:123], s[76:77]
	v_pk_mul_f32 v[124:125], v[124:125], s[76:77]
	v_pk_mul_f32 v[126:127], v[126:127], s[76:77]
	v_exp_f32_e32 v127, v127
	v_exp_f32_e32 v120, v120
	v_exp_f32_e32 v121, v121
	v_exp_f32_e32 v122, v122
	v_exp_f32_e32 v123, v123
	v_exp_f32_e32 v124, v124
	v_exp_f32_e32 v125, v125
	v_exp_f32_e32 v126, v126
	v_pk_add_f32 v[120:121], v[120:121], s[86:87]
	v_pk_add_f32 v[122:123], v[122:123], s[86:87]
	v_pk_add_f32 v[124:125], v[124:125], s[86:87]
	v_pk_add_f32 v[126:127], v[126:127], s[86:87]
	v_rcp_f32_e32 v127, v127
	v_rcp_f32_e32 v120, v120
	v_rcp_f32_e32 v121, v121
	v_rcp_f32_e32 v122, v122
	v_rcp_f32_e32 v123, v123
	v_rcp_f32_e32 v124, v124
	v_rcp_f32_e32 v125, v125
	v_rcp_f32_e32 v126, v126
	v_pk_mul_f32 v[116:117], v[116:117], v[120:121]
	v_pk_mul_f32 v[118:119], v[118:119], v[122:123]
	v_pk_mul_f32 v[112:113], v[112:113], v[124:125]
	v_pk_mul_f32 v[114:115], v[114:115], v[126:127]
	v_cvt_pk_bf16_f32 v120, v116, v117
	v_cvt_pk_bf16_f32 v121, v118, v119
	v_cvt_pk_bf16_f32 v122, v112, v113
	v_cvt_pk_bf16_f32 v123, v114, v115
	global_store_dwordx4 v[174:175], v[120:123], off
	s_nop 0
	s_nop 0
	v_or_b32_e32 v112, 32, v160
	v_mad_i64_i32 v[114:115], s[0:1], v176, s65, v[164:165]
	v_lshl_add_u64 v[114:115], v[114:115], 0, v[166:167]
	v_fmamk_f32 v113, v182, 0x3a800000, v172
	v_rsq_f32_e32 v116, v113
	v_ashrrev_i32_e32 v113, 31, v112
	v_lshl_add_u64 v[118:119], v[112:113], 2, s[10:11]
	v_pk_fma_f32 v[106:107], v[106:107], v[116:117], v[138:139] op_sel_hi:[1,0,1]
	v_pk_fma_f32 v[98:99], v[98:99], v[116:117], v[130:131] op_sel_hi:[1,0,1]
	v_pk_fma_f32 v[110:111], v[110:111], v[116:117], v[142:143] op_sel_hi:[1,0,1]
	v_pk_fma_f32 v[108:109], v[108:109], v[116:117], v[140:141] op_sel_hi:[1,0,1]
	v_pk_fma_f32 v[104:105], v[104:105], v[116:117], v[136:137] op_sel_hi:[1,0,1]
	v_pk_fma_f32 v[102:103], v[102:103], v[116:117], v[134:135] op_sel_hi:[1,0,1]
	v_pk_fma_f32 v[100:101], v[100:101], v[116:117], v[132:133] op_sel_hi:[1,0,1]
	v_pk_fma_f32 v[96:97], v[96:97], v[116:117], v[128:129] op_sel_hi:[1,0,1]
	v_pk_mul_f32 v[100:101], v[108:109], v[100:101]
	v_pk_mul_f32 v[102:103], v[110:111], v[102:103]
	v_pk_mul_f32 v[96:97], v[104:105], v[96:97]
	v_pk_mul_f32 v[98:99], v[106:107], v[98:99]
	v_pk_mul_f32 v[108:109], v[108:109], s[76:77]
	v_pk_mul_f32 v[110:111], v[110:111], s[76:77]
	v_pk_mul_f32 v[104:105], v[104:105], s[76:77]
	v_pk_mul_f32 v[106:107], v[106:107], s[76:77]
	v_exp_f32_e32 v107, v107
	v_exp_f32_e32 v108, v108
	v_exp_f32_e32 v109, v109
	v_exp_f32_e32 v110, v110
	v_exp_f32_e32 v111, v111
	v_exp_f32_e32 v104, v104
	v_exp_f32_e32 v105, v105
	v_exp_f32_e32 v106, v106
	v_pk_add_f32 v[108:109], v[108:109], s[86:87]
	v_pk_add_f32 v[110:111], v[110:111], s[86:87]
	v_pk_add_f32 v[104:105], v[104:105], s[86:87]
	v_pk_add_f32 v[106:107], v[106:107], s[86:87]
	v_rcp_f32_e32 v107, v107
	v_rcp_f32_e32 v108, v108
	v_rcp_f32_e32 v109, v109
; __device__ __forceinline__ unsigned cvt_pk_bf16(float lo, float hi) { unsigned r; asm volatile("v_cvt_pk_bf16_f32 %0, %1, %2" : "=v"(r) : "v"(lo), "v"(hi)); return r; }
;     __device__ __forceinline__ static float sg(float g, float u) { return g * u * __builtin_amdgcn_rcpf(1.0f + __builtin_amdgcn_exp2f(-1.4426950408889634f * g)); }
;     __device__ __forceinline__ void operator()(const f32x4 (&acc)[2][2][4][2], const Unit& u, int wr, int wc, int fr, int fq) const {
;         const int row0 = u.pm * BM + wr * 64 + fr, col0 = u.pn * BM + wc * 32 + 8 * fq, j0 = u.pn * HALF + wc * 32 + 8 * fq;
;         const float* bp = bt + (size_t)((u.pm * BM) >> 12) * (2 * 2816) + col0;
;         f32x4 bv[2][2];
; #pragma unroll
;         for (int bj = 0; bj < 2; ++bj)
; #pragma unroll
;             for (int n = 0; n < 2; ++n) bv[bj][n] = *(const f32x4*)(bp + bj * HALF + 4 * n);
; #pragma unroll
;         for (int ai = 0; ai < 2; ++ai)
; #pragma unroll
;             for (int m = 0; m < 4; ++m) { const int row = row0 + ai * HALF + m * 16;
;                 const float rstd = __builtin_amdgcn_rsqf(SS[row] * (1.0f / 1024.0f) + 1e-6f);
;                 const f32x4 g0 = acc[ai][0][m][0] * rstd + bv[0][0], g1 = acc[ai][0][m][1] * rstd + bv[0][1], u0 = acc[ai][1][m][0] * rstd + bv[1][0], u1 = acc[ai][1][m][1] * rstd + bv[1][1];
;                 u32x4 w; w.x = cvt_pk_bf16(sg(g0[0], u0[0]), sg(g0[1], u0[1])); w.y = cvt_pk_bf16(sg(g0[2], u0[2]), sg(g0[3], u0[3]));
;                 w.z = cvt_pk_bf16(sg(g1[0], u1[0]), sg(g1[1], u1[1])); w.w = cvt_pk_bf16(sg(g1[2], u1[2]), sg(g1[3], u1[3]));
;                 *(u32x4*)(O + (size_t)row * ldc + j0) = w; }
	v_rcp_f32_e32 v110, v110
	v_rcp_f32_e32 v111, v111
	v_rcp_f32_e32 v104, v104
	v_rcp_f32_e32 v105, v105
	v_rcp_f32_e32 v106, v106
	v_pk_mul_f32 v[100:101], v[100:101], v[108:109]
	v_pk_mul_f32 v[102:103], v[102:103], v[110:111]
	v_pk_mul_f32 v[96:97], v[96:97], v[104:105]
	v_pk_mul_f32 v[98:99], v[98:99], v[106:107]
	v_cvt_pk_bf16_f32 v104, v100, v101
	v_cvt_pk_bf16_f32 v105, v102, v103
	v_cvt_pk_bf16_f32 v106, v96, v97
	v_cvt_pk_bf16_f32 v107, v98, v99
	global_store_dwordx4 v[114:115], v[104:107], off
	s_nop 0
	s_nop 0
	v_or_b32_e32 v96, 48, v160
	v_mad_i64_i32 v[98:99], s[0:1], v112, s65, v[164:165]
	v_lshl_add_u64 v[98:99], v[98:99], 0, v[166:167]
	v_fmamk_f32 v97, v183, 0x3a800000, v172
	v_rsq_f32_e32 v100, v97
	v_ashrrev_i32_e32 v97, 31, v96
	v_lshl_add_u64 v[102:103], v[96:97], 2, s[10:11]
	v_pk_fma_f32 v[90:91], v[90:91], v[100:101], v[138:139] op_sel_hi:[1,0,1]
	v_pk_fma_f32 v[82:83], v[82:83], v[100:101], v[130:131] op_sel_hi:[1,0,1]
	v_pk_fma_f32 v[94:95], v[94:95], v[100:101], v[142:143] op_sel_hi:[1,0,1]
	v_pk_fma_f32 v[92:93], v[92:93], v[100:101], v[140:141] op_sel_hi:[1,0,1]
	v_pk_fma_f32 v[88:89], v[88:89], v[100:101], v[136:137] op_sel_hi:[1,0,1]
	v_pk_fma_f32 v[86:87], v[86:87], v[100:101], v[134:135] op_sel_hi:[1,0,1]
	v_pk_fma_f32 v[84:85], v[84:85], v[100:101], v[132:133] op_sel_hi:[1,0,1]
	v_pk_fma_f32 v[80:81], v[80:81], v[100:101], v[128:129] op_sel_hi:[1,0,1]
	v_pk_mul_f32 v[84:85], v[92:93], v[84:85]
	v_pk_mul_f32 v[86:87], v[94:95], v[86:87]
	v_pk_mul_f32 v[80:81], v[88:89], v[80:81]
	v_pk_mul_f32 v[82:83], v[90:91], v[82:83]
	v_pk_mul_f32 v[92:93], v[92:93], s[76:77]
	v_pk_mul_f32 v[94:95], v[94:95], s[76:77]
	v_pk_mul_f32 v[88:89], v[88:89], s[76:77]
	v_pk_mul_f32 v[90:91], v[90:91], s[76:77]
	v_exp_f32_e32 v91, v91
	v_exp_f32_e32 v92, v92
	v_exp_f32_e32 v93, v93
	v_exp_f32_e32 v94, v94
	v_exp_f32_e32 v95, v95
	v_exp_f32_e32 v88, v88
	v_exp_f32_e32 v89, v89
	v_exp_f32_e32 v90, v90
	v_pk_add_f32 v[92:93], v[92:93], s[86:87]
	v_pk_add_f32 v[94:95], v[94:95], s[86:87]
	v_pk_add_f32 v[88:89], v[88:89], s[86:87]
	v_pk_add_f32 v[90:91], v[90:91], s[86:87]
	v_rcp_f32_e32 v91, v91
	v_rcp_f32_e32 v92, v92
	v_rcp_f32_e32 v93, v93
	v_rcp_f32_e32 v94, v94
	v_rcp_f32_e32 v95, v95
	v_rcp_f32_e32 v88, v88
	v_rcp_f32_e32 v89, v89
	v_rcp_f32_e32 v90, v90
	v_pk_mul_f32 v[84:85], v[84:85], v[92:93]
	v_pk_mul_f32 v[86:87], v[86:87], v[94:95]
	v_pk_mul_f32 v[80:81], v[80:81], v[88:89]
	v_pk_mul_f32 v[82:83], v[82:83], v[90:91]
	v_cvt_pk_bf16_f32 v88, v84, v85
	v_cvt_pk_bf16_f32 v89, v86, v87
	v_cvt_pk_bf16_f32 v90, v80, v81
	v_cvt_pk_bf16_f32 v91, v82, v83
	global_store_dwordx4 v[98:99], v[88:91], off
	s_nop 0
	s_nop 0
	v_mad_i64_i32 v[82:83], s[0:1], v96, s65, v[164:165]
	v_lshl_add_u64 v[82:83], v[82:83], 0, v[166:167]
	v_fmamk_f32 v80, v184, 0x3a800000, v172
	v_rsq_f32_e32 v80, v80
	s_nop 0
	v_pk_fma_f32 v[74:75], v[74:75], v[80:81], v[138:139] op_sel_hi:[1,0,1]
	v_pk_fma_f32 v[66:67], v[66:67], v[80:81], v[130:131] op_sel_hi:[1,0,1]
	v_pk_fma_f32 v[78:79], v[78:79], v[80:81], v[142:143] op_sel_hi:[1,0,1]
	v_pk_fma_f32 v[76:77], v[76:77], v[80:81], v[140:141] op_sel_hi:[1,0,1]
	v_pk_fma_f32 v[72:73], v[72:73], v[80:81], v[136:137] op_sel_hi:[1,0,1]
	v_pk_fma_f32 v[70:71], v[70:71], v[80:81], v[134:135] op_sel_hi:[1,0,1]
	v_pk_fma_f32 v[68:69], v[68:69], v[80:81], v[132:133] op_sel_hi:[1,0,1]
	v_pk_fma_f32 v[64:65], v[64:65], v[80:81], v[128:129] op_sel_hi:[1,0,1]
	v_pk_mul_f32 v[68:69], v[76:77], v[68:69]
	v_pk_mul_f32 v[70:71], v[78:79], v[70:71]
	v_pk_mul_f32 v[64:65], v[72:73], v[64:65]
	v_pk_mul_f32 v[66:67], v[74:75], v[66:67]
	v_pk_mul_f32 v[76:77], v[76:77], s[76:77]
	v_pk_mul_f32 v[78:79], v[78:79], s[76:77]
	v_pk_mul_f32 v[72:73], v[72:73], s[76:77]
	v_pk_mul_f32 v[74:75], v[74:75], s[76:77]
	v_exp_f32_e32 v75, v75
	v_exp_f32_e32 v76, v76
	v_exp_f32_e32 v77, v77
	v_exp_f32_e32 v78, v78
	v_exp_f32_e32 v79, v79
	v_exp_f32_e32 v72, v72
	v_exp_f32_e32 v73, v73
	v_exp_f32_e32 v74, v74
	v_pk_add_f32 v[76:77], v[76:77], s[86:87]
	v_pk_add_f32 v[78:79], v[78:79], s[86:87]
	v_pk_add_f32 v[72:73], v[72:73], s[86:87]
	v_pk_add_f32 v[74:75], v[74:75], s[86:87]
	v_rcp_f32_e32 v75, v75
	v_rcp_f32_e32 v76, v76
	v_rcp_f32_e32 v77, v77
	v_rcp_f32_e32 v78, v78
	v_rcp_f32_e32 v79, v79
	v_rcp_f32_e32 v72, v72
	v_rcp_f32_e32 v73, v73
	v_rcp_f32_e32 v74, v74
	v_pk_mul_f32 v[68:69], v[68:69], v[76:77]
	v_pk_mul_f32 v[70:71], v[70:71], v[78:79]
	v_pk_mul_f32 v[64:65], v[64:65], v[72:73]
	v_pk_mul_f32 v[66:67], v[66:67], v[74:75]
	v_cvt_pk_bf16_f32 v72, v68, v69
	v_cvt_pk_bf16_f32 v73, v70, v71
	v_cvt_pk_bf16_f32 v74, v64, v65
	v_cvt_pk_bf16_f32 v75, v66, v67
	global_store_dwordx4 v[82:83], v[72:75], off
	s_nop 0
	s_nop 0
	v_add_u32_e32 v65, 0x80, v160
	v_mad_i64_i32 v[66:67], s[0:1], v65, s65, v[164:165]
	v_lshl_add_u64 v[66:67], v[66:67], 0, v[166:167]
	v_fmamk_f32 v64, v185, 0x3a800000, v172
	v_rsq_f32_e32 v64, v64
	s_nop 0
	v_pk_fma_f32 v[58:59], v[58:59], v[64:65], v[138:139] op_sel_hi:[1,0,1]
	v_pk_fma_f32 v[50:51], v[50:51], v[64:65], v[130:131] op_sel_hi:[1,0,1]
	v_pk_fma_f32 v[62:63], v[62:63], v[64:65], v[142:143] op_sel_hi:[1,0,1]
	v_pk_fma_f32 v[60:61], v[60:61], v[64:65], v[140:141] op_sel_hi:[1,0,1]
	v_pk_fma_f32 v[56:57], v[56:57], v[64:65], v[136:137] op_sel_hi:[1,0,1]
	v_pk_fma_f32 v[54:55], v[54:55], v[64:65], v[134:135] op_sel_hi:[1,0,1]
	v_pk_fma_f32 v[52:53], v[52:53], v[64:65], v[132:133] op_sel_hi:[1,0,1]
	v_pk_fma_f32 v[48:49], v[48:49], v[64:65], v[128:129] op_sel_hi:[1,0,1]
	v_pk_mul_f32 v[52:53], v[60:61], v[52:53]
	v_pk_mul_f32 v[54:55], v[62:63], v[54:55]
	v_pk_mul_f32 v[48:49], v[56:57], v[48:49]
; __device__ __forceinline__ unsigned cvt_pk_bf16(float lo, float hi) { unsigned r; asm volatile("v_cvt_pk_bf16_f32 %0, %1, %2" : "=v"(r) : "v"(lo), "v"(hi)); return r; }
;     __device__ __forceinline__ static float sg(float g, float u) { return g * u * __builtin_amdgcn_rcpf(1.0f + __builtin_amdgcn_exp2f(-1.4426950408889634f * g)); }
;     __device__ __forceinline__ void operator()(const f32x4 (&acc)[2][2][4][2], const Unit& u, int wr, int wc, int fr, int fq) const {
;         const int row0 = u.pm * BM + wr * 64 + fr, col0 = u.pn * BM + wc * 32 + 8 * fq, j0 = u.pn * HALF + wc * 32 + 8 * fq;
;         const float* bp = bt + (size_t)((u.pm * BM) >> 12) * (2 * 2816) + col0;
;         f32x4 bv[2][2];
; #pragma unroll
;         for (int bj = 0; bj < 2; ++bj)
; #pragma unroll
;             for (int n = 0; n < 2; ++n) bv[bj][n] = *(const f32x4*)(bp + bj * HALF + 4 * n);
; #pragma unroll
;         for (int ai = 0; ai < 2; ++ai)
; #pragma unroll
;             for (int m = 0; m < 4; ++m) { const int row = row0 + ai * HALF + m * 16;
;                 const float rstd = __builtin_amdgcn_rsqf(SS[row] * (1.0f / 1024.0f) + 1e-6f);
;                 const f32x4 g0 = acc[ai][0][m][0] * rstd + bv[0][0], g1 = acc[ai][0][m][1] * rstd + bv[0][1], u0 = acc[ai][1][m][0] * rstd + bv[1][0], u1 = acc[ai][1][m][1] * rstd + bv[1][1];
;                 u32x4 w; w.x = cvt_pk_bf16(sg(g0[0], u0[0]), sg(g0[1], u0[1])); w.y = cvt_pk_bf16(sg(g0[2], u0[2]), sg(g0[3], u0[3]));
;                 w.z = cvt_pk_bf16(sg(g1[0], u1[0]), sg(g1[1], u1[1])); w.w = cvt_pk_bf16(sg(g1[2], u1[2]), sg(g1[3], u1[3]));
;                 *(u32x4*)(O + (size_t)row * ldc + j0) = w; }
	v_pk_mul_f32 v[50:51], v[58:59], v[50:51]
	v_pk_mul_f32 v[60:61], v[60:61], s[76:77]
	v_pk_mul_f32 v[62:63], v[62:63], s[76:77]
	v_pk_mul_f32 v[56:57], v[56:57], s[76:77]
	v_pk_mul_f32 v[58:59], v[58:59], s[76:77]
	v_exp_f32_e32 v59, v59
	v_exp_f32_e32 v60, v60
	v_exp_f32_e32 v61, v61
	v_exp_f32_e32 v62, v62
	v_exp_f32_e32 v63, v63
	v_exp_f32_e32 v56, v56
	v_exp_f32_e32 v57, v57
	v_exp_f32_e32 v58, v58
	v_pk_add_f32 v[60:61], v[60:61], s[86:87]
	v_pk_add_f32 v[62:63], v[62:63], s[86:87]
	v_pk_add_f32 v[56:57], v[56:57], s[86:87]
	v_pk_add_f32 v[58:59], v[58:59], s[86:87]
	v_rcp_f32_e32 v59, v59
	v_rcp_f32_e32 v60, v60
	v_rcp_f32_e32 v61, v61
	v_rcp_f32_e32 v62, v62
	v_rcp_f32_e32 v63, v63
	v_rcp_f32_e32 v56, v56
	v_rcp_f32_e32 v57, v57
	v_rcp_f32_e32 v58, v58
	v_pk_mul_f32 v[52:53], v[52:53], v[60:61]
	v_pk_mul_f32 v[54:55], v[54:55], v[62:63]
	v_pk_mul_f32 v[48:49], v[48:49], v[56:57]
	v_pk_mul_f32 v[50:51], v[50:51], v[58:59]
	v_cvt_pk_bf16_f32 v56, v52, v53
	v_cvt_pk_bf16_f32 v57, v54, v55
	v_cvt_pk_bf16_f32 v58, v48, v49
	v_cvt_pk_bf16_f32 v59, v50, v51
	global_store_dwordx4 v[66:67], v[56:59], off
	s_nop 0
	s_nop 0
	v_add_u32_e32 v49, 0x90, v160
	v_mad_i64_i32 v[50:51], s[0:1], v49, s65, v[164:165]
	v_lshl_add_u64 v[50:51], v[50:51], 0, v[166:167]
	v_fmamk_f32 v48, v186, 0x3a800000, v172
	v_rsq_f32_e32 v48, v48
	s_nop 0
	v_pk_fma_f32 v[42:43], v[42:43], v[48:49], v[138:139] op_sel_hi:[1,0,1]
	v_pk_fma_f32 v[34:35], v[34:35], v[48:49], v[130:131] op_sel_hi:[1,0,1]
	v_pk_fma_f32 v[46:47], v[46:47], v[48:49], v[142:143] op_sel_hi:[1,0,1]
	v_pk_fma_f32 v[44:45], v[44:45], v[48:49], v[140:141] op_sel_hi:[1,0,1]
	v_pk_fma_f32 v[40:41], v[40:41], v[48:49], v[136:137] op_sel_hi:[1,0,1]
	v_pk_fma_f32 v[38:39], v[38:39], v[48:49], v[134:135] op_sel_hi:[1,0,1]
	v_pk_fma_f32 v[36:37], v[36:37], v[48:49], v[132:133] op_sel_hi:[1,0,1]
	v_pk_fma_f32 v[32:33], v[32:33], v[48:49], v[128:129] op_sel_hi:[1,0,1]
	v_pk_mul_f32 v[36:37], v[44:45], v[36:37]
	v_pk_mul_f32 v[38:39], v[46:47], v[38:39]
	v_pk_mul_f32 v[32:33], v[40:41], v[32:33]
	v_pk_mul_f32 v[34:35], v[42:43], v[34:35]
	v_pk_mul_f32 v[44:45], v[44:45], s[76:77]
	v_pk_mul_f32 v[46:47], v[46:47], s[76:77]
	v_pk_mul_f32 v[40:41], v[40:41], s[76:77]
	v_pk_mul_f32 v[42:43], v[42:43], s[76:77]
	v_exp_f32_e32 v43, v43
	v_exp_f32_e32 v44, v44
	v_exp_f32_e32 v45, v45
	v_exp_f32_e32 v46, v46
	v_exp_f32_e32 v47, v47
	v_exp_f32_e32 v40, v40
	v_exp_f32_e32 v41, v41
	v_exp_f32_e32 v42, v42
	v_pk_add_f32 v[44:45], v[44:45], s[86:87]
	v_pk_add_f32 v[46:47], v[46:47], s[86:87]
	v_pk_add_f32 v[40:41], v[40:41], s[86:87]
	v_pk_add_f32 v[42:43], v[42:43], s[86:87]
	v_rcp_f32_e32 v43, v43
	v_rcp_f32_e32 v44, v44
	v_rcp_f32_e32 v45, v45
	v_rcp_f32_e32 v46, v46
	v_rcp_f32_e32 v47, v47
	v_rcp_f32_e32 v40, v40
	v_rcp_f32_e32 v41, v41
	v_rcp_f32_e32 v42, v42
	v_pk_mul_f32 v[36:37], v[36:37], v[44:45]
	v_pk_mul_f32 v[38:39], v[38:39], v[46:47]
	v_pk_mul_f32 v[32:33], v[32:33], v[40:41]
	v_pk_mul_f32 v[34:35], v[34:35], v[42:43]
	v_cvt_pk_bf16_f32 v40, v36, v37
	v_cvt_pk_bf16_f32 v41, v38, v39
	v_cvt_pk_bf16_f32 v42, v32, v33
	v_cvt_pk_bf16_f32 v43, v34, v35
	global_store_dwordx4 v[50:51], v[40:43], off
	s_nop 0
	s_nop 0
	v_add_u32_e32 v33, 0xa0, v160
	v_mad_i64_i32 v[34:35], s[0:1], v33, s65, v[164:165]
	v_lshl_add_u64 v[34:35], v[34:35], 0, v[166:167]
	v_fmamk_f32 v32, v187, 0x3a800000, v172
	v_rsq_f32_e32 v32, v32
	s_nop 0
	v_pk_fma_f32 v[26:27], v[26:27], v[32:33], v[138:139] op_sel_hi:[1,0,1]
	v_pk_fma_f32 v[18:19], v[18:19], v[32:33], v[130:131] op_sel_hi:[1,0,1]
	v_pk_fma_f32 v[30:31], v[30:31], v[32:33], v[142:143] op_sel_hi:[1,0,1]
	v_pk_fma_f32 v[28:29], v[28:29], v[32:33], v[140:141] op_sel_hi:[1,0,1]
; #define PG8_BAR __builtin_amdgcn_s_barrier()
; template <class Epi, class Sched, bool ALIGN_EPI = false, bool SP2 = false>
; __device__ __forceinline__ void gemm_phase(PG8_LAS unsigned char* lds, const Gemm g, const Sched& S, const Epi& E) {
;     ...
;         if constexpr (ALIGN_EPI) { if (wr == 0) PG8_BAR; }
;         if constexpr (!Epi::AFTER_DRAIN) { int l2_ = threadIdx.x; asm volatile("" : "+v"(l2_)); l2_ &= 63; E(acc, cur, wr, wc, l2_ & 15, l2_ >> 4); S.done(cur); }
;         if (!has_next) break;
; #pragma unroll
;         for (int a = 0; a < 2; ++a)
; #pragma unroll
;             for (int b = 0; b < 2; ++b)
; #pragma unroll
;                 for (int m = 0; m < 4; ++m)
; #pragma unroll
;                     for (int n = 0; n < 2; ++n) acc[a][b][m][n] = (f32x4){0.f, 0.f, 0.f, 0.f};
;         cur = nxt; cA = nA; cB = nB; ++ui;
;         if constexpr (ALIGN_EPI) { if (wr == 1) PG8_BAR; }
;     __device__ __forceinline__ static float sg(float g, float u) { return g * u * __builtin_amdgcn_rcpf(1.0f + __builtin_amdgcn_exp2f(-1.4426950408889634f * g)); }
;     __device__ __forceinline__ void operator()(const f32x4 (&acc)[2][2][4][2], const Unit& u, int wr, int wc, int fr, int fq) const {
;         const int row0 = u.pm * BM + wr * 64 + fr, col0 = u.pn * BM + wc * 32 + 8 * fq, j0 = u.pn * HALF + wc * 32 + 8 * fq;
;         const float* bp = bt + (size_t)((u.pm * BM) >> 12) * (2 * 2816) + col0;
;         f32x4 bv[2][2];
; #pragma unroll
;         for (int bj = 0; bj < 2; ++bj)
; #pragma unroll
;             for (int n = 0; n < 2; ++n) bv[bj][n] = *(const f32x4*)(bp + bj * HALF + 4 * n);
; #pragma unroll
;         for (int ai = 0; ai < 2; ++ai)
; #pragma unroll
;             for (int m = 0; m < 4; ++m) { const int row = row0 + ai * HALF + m * 16;
;                 const float rstd = __builtin_amdgcn_rsqf(SS[row] * (1.0f / 1024.0f) + 1e-6f);
;                 const f32x4 g0 = acc[ai][0][m][0] * rstd + bv[0][0], g1 = acc[ai][0][m][1] * rstd + bv[0][1], u0 = acc[ai][1][m][0] * rstd + bv[1][0], u1 = acc[ai][1][m][1] * rstd + bv[1][1];
;                 u32x4 w; w.x = cvt_pk_bf16(sg(g0[0], u0[0]), sg(g0[1], u0[1])); w.y = cvt_pk_bf16(sg(g0[2], u0[2]), sg(g0[3], u0[3]));
;                 w.z = cvt_pk_bf16(sg(g1[0], u1[0]), sg(g1[1], u1[1])); w.w = cvt_pk_bf16(sg(g1[2], u1[2]), sg(g1[3], u1[3]));
;                 *(u32x4*)(O + (size_t)row * ldc + j0) = w; }
	v_pk_fma_f32 v[24:25], v[24:25], v[32:33], v[136:137] op_sel_hi:[1,0,1]
	v_pk_fma_f32 v[22:23], v[22:23], v[32:33], v[134:135] op_sel_hi:[1,0,1]
	v_pk_fma_f32 v[20:21], v[20:21], v[32:33], v[132:133] op_sel_hi:[1,0,1]
	v_pk_fma_f32 v[16:17], v[16:17], v[32:33], v[128:129] op_sel_hi:[1,0,1]
	v_pk_mul_f32 v[20:21], v[28:29], v[20:21]
	v_pk_mul_f32 v[22:23], v[30:31], v[22:23]
	v_pk_mul_f32 v[16:17], v[24:25], v[16:17]
	v_pk_mul_f32 v[18:19], v[26:27], v[18:19]
	v_pk_mul_f32 v[28:29], v[28:29], s[76:77]
	v_pk_mul_f32 v[30:31], v[30:31], s[76:77]
	v_pk_mul_f32 v[24:25], v[24:25], s[76:77]
	v_pk_mul_f32 v[26:27], v[26:27], s[76:77]
	v_exp_f32_e32 v27, v27
	v_exp_f32_e32 v28, v28
	v_exp_f32_e32 v29, v29
	v_exp_f32_e32 v30, v30
	v_exp_f32_e32 v31, v31
	v_exp_f32_e32 v24, v24
	v_exp_f32_e32 v25, v25
	v_exp_f32_e32 v26, v26
	v_pk_add_f32 v[28:29], v[28:29], s[86:87]
	v_pk_add_f32 v[30:31], v[30:31], s[86:87]
	v_pk_add_f32 v[24:25], v[24:25], s[86:87]
	v_pk_add_f32 v[26:27], v[26:27], s[86:87]
	v_rcp_f32_e32 v27, v27
	v_rcp_f32_e32 v28, v28
	v_rcp_f32_e32 v29, v29
	v_rcp_f32_e32 v30, v30
	v_rcp_f32_e32 v31, v31
	v_rcp_f32_e32 v24, v24
	v_rcp_f32_e32 v25, v25
	v_rcp_f32_e32 v26, v26
	v_pk_mul_f32 v[20:21], v[20:21], v[28:29]
	v_pk_mul_f32 v[22:23], v[22:23], v[30:31]
	v_pk_mul_f32 v[16:17], v[16:17], v[24:25]
	v_pk_mul_f32 v[18:19], v[18:19], v[26:27]
	v_cvt_pk_bf16_f32 v24, v20, v21
	v_cvt_pk_bf16_f32 v25, v22, v23
	v_cvt_pk_bf16_f32 v26, v16, v17
	v_cvt_pk_bf16_f32 v27, v18, v19
	global_store_dwordx4 v[34:35], v[24:27], off
	s_nop 0
	s_nop 0
	v_add_u32_e32 v17, 0xb0, v160
	v_mad_i64_i32 v[18:19], s[0:1], v17, s65, v[164:165]
	v_lshl_add_u64 v[18:19], v[18:19], 0, v[166:167]
	v_fmamk_f32 v16, v188, 0x3a800000, v172
	v_rsq_f32_e32 v16, v16
	s_nop 0
	v_pk_fma_f32 v[10:11], v[10:11], v[16:17], v[138:139] op_sel_hi:[1,0,1]
	v_pk_fma_f32 v[2:3], v[2:3], v[16:17], v[130:131] op_sel_hi:[1,0,1]
	v_pk_fma_f32 v[14:15], v[14:15], v[16:17], v[142:143] op_sel_hi:[1,0,1]
	v_pk_fma_f32 v[12:13], v[12:13], v[16:17], v[140:141] op_sel_hi:[1,0,1]
	v_pk_fma_f32 v[8:9], v[8:9], v[16:17], v[136:137] op_sel_hi:[1,0,1]
	v_pk_fma_f32 v[6:7], v[6:7], v[16:17], v[134:135] op_sel_hi:[1,0,1]
	v_pk_fma_f32 v[4:5], v[4:5], v[16:17], v[132:133] op_sel_hi:[1,0,1]
	v_pk_fma_f32 v[0:1], v[0:1], v[16:17], v[128:129] op_sel_hi:[1,0,1]
	v_pk_mul_f32 v[4:5], v[12:13], v[4:5]
	v_pk_mul_f32 v[6:7], v[14:15], v[6:7]
	v_pk_mul_f32 v[0:1], v[8:9], v[0:1]
	v_pk_mul_f32 v[2:3], v[10:11], v[2:3]
	v_pk_mul_f32 v[12:13], v[12:13], s[76:77]
	v_pk_mul_f32 v[14:15], v[14:15], s[76:77]
	v_pk_mul_f32 v[8:9], v[8:9], s[76:77]
	v_pk_mul_f32 v[10:11], v[10:11], s[76:77]
	v_exp_f32_e32 v11, v11
	v_exp_f32_e32 v12, v12
	v_exp_f32_e32 v13, v13
	v_exp_f32_e32 v14, v14
	v_exp_f32_e32 v15, v15
	v_exp_f32_e32 v8, v8
	v_exp_f32_e32 v9, v9
	v_exp_f32_e32 v10, v10
	v_pk_add_f32 v[12:13], v[12:13], s[86:87]
	v_pk_add_f32 v[14:15], v[14:15], s[86:87]
	v_pk_add_f32 v[8:9], v[8:9], s[86:87]
	v_pk_add_f32 v[10:11], v[10:11], s[86:87]
	v_rcp_f32_e32 v11, v11
	v_rcp_f32_e32 v12, v12
	v_rcp_f32_e32 v13, v13
	v_rcp_f32_e32 v14, v14
	v_rcp_f32_e32 v15, v15
	v_rcp_f32_e32 v8, v8
	v_rcp_f32_e32 v9, v9
	v_rcp_f32_e32 v10, v10
	v_pk_mul_f32 v[4:5], v[4:5], v[12:13]
	v_pk_mul_f32 v[6:7], v[6:7], v[14:15]
	v_pk_mul_f32 v[0:1], v[0:1], v[8:9]
	v_pk_mul_f32 v[2:3], v[2:3], v[10:11]
	v_cvt_pk_bf16_f32 v8, v4, v5
	v_cvt_pk_bf16_f32 v9, v6, v7
	v_cvt_pk_bf16_f32 v10, v0, v1
	v_cvt_pk_bf16_f32 v11, v2, v3
	global_store_dwordx4 v[18:19], v[8:11], off
	s_cbranch_vccnz .LBB0_1300
	s_andn2_b64 vcc, exec, s[26:27]
	s_cbranch_vccnz .LBB0_1299
	s_barrier
	s_branch .LBB0_1299
